# diff attention loop: row sums via 16x16x32 bf16 MFMA (ones-selector B), no in-loop v_add_f32
# baseline (speedup 1.0000x reference)
; #define LAS __attribute__((address_space(3)))
; #define WAIT_BAR() asm volatile("s_waitcnt vmcnt(0) lgkmcnt(0)\n\ts_barrier" ::: "memory")
; #define BMODE(t) do { if constexpr (DIFF) { const int dd = (t) * 64 - qw; float cbn; if (dd <= -191) { bm = 1; cbn = bL; } else if (dd >= 159) { bm = 1; cbn = bR; } else { bm = 2; cbn = 0.f; } \
;             ix = dd - r32 + 256 + 4 * hi; if (cbn != cb) { cb = cbn; moved = true; } } } while (0)
; #define NEGM() do { if (moved) { const float v_ = cb - m_reg; _Pragma("unroll") for (int r = 0; r < 16; ++r) negm[r] = v_; asm volatile("" : "+v"(negm)); } } while (0)
; #define WAIT_BAR() asm volatile("s_waitcnt vmcnt(0) lgkmcnt(0)\n\ts_barrier" ::: "memory")
; #define MFMA32(a, b, c) __builtin_amdgcn_mfma_f32_32x32x16_bf16(a, b, c, 0, 0, 0)
; #define BMODE(t) do { if constexpr (DIFF) { const int dd = (t) * 64 - qw; float cbn; if (dd <= -191) { bm = 1; cbn = bL; } else if (dd >= 159) { bm = 1; cbn = bR; } else { bm = 2; cbn = 0.f; } \
;             ix = dd - r32 + 256 + 4 * hi; if (cbn != cb) { cb = cbn; moved = true; } } } while (0)
; template <int NCB, bool DIFF, bool STAT>
; __device__ __forceinline__ void attn_unit(LAS char* lds, const Params& P, int s, int head, int qb, float sref) {
;     ...
;         f32x16 negm;
; #pragma unroll
;         for (int d = 0; d < NCB; ++d) o[d] = f32x16{};
;         f32x16 pA0, pA1, pB0, pB1; float alA = 1.f, alB = 1.f;
;         u32x4 pw[4];
;         int bm = 0, ix = 0;
;         WAIT_BAR();
;         BMODE(0); NEGM();
;         { const LAS char* kp_ = kp0;
; #pragma unroll
;           for (int d0 = 0; d0 < 4; ++d0) { const bf16x8 b0 = *(const LAS bf16x8*)(kp_ + d0 * 2048), b1 = *(const LAS bf16x8*)(kp_ + d0 * 2048 + 512);
;               if (d0 == 0) { if constexpr (ZREF) { pA0 = MFMA32(b0, qr[0], f32x16{}); pA1 = MFMA32(b1, qr[0], f32x16{}); } else { pA0 = MFMA32(b0, qr[0], negm); pA1 = MFMA32(b1, qr[0], negm); } } else { pA0 = MFMA32(b0, qr[d0], pA0); pA1 = MFMA32(b1, qr[d0], pA1); } } }
;         bias_add<DIFF>(pA0, pA1, bm, tab, ix);
;         if constexpr (!STAT) rowmax_decide<DIFF, true>(pA0, pA1, m_reg, alA, moved, bm, tab, ix); else moved = false;
; #pragma unroll
;         for (int r = 0; r < 16; ++r) { pA0[r] = __builtin_amdgcn_exp2f(pA0[r]); pA1[r] = __builtin_amdgcn_exp2f(pA1[r]); }
;         int sl_prev = 0, sl_cur = 1;
.LBB0_511:
	s_nop 10
	v_exp_f32_e32 v82, v18
	v_exp_f32_e32 v83, v19
	v_exp_f32_e32 v84, v20
	v_exp_f32_e32 v85, v21
	v_exp_f32_e32 v86, v22
	v_exp_f32_e32 v87, v23
	v_exp_f32_e32 v88, v24
	v_exp_f32_e32 v89, v25
	v_exp_f32_e32 v90, v26
	v_exp_f32_e32 v91, v27
	v_exp_f32_e32 v92, v28
	v_exp_f32_e32 v93, v29
	v_exp_f32_e32 v94, v30
	v_exp_f32_e32 v95, v31
	v_exp_f32_e32 v96, v32
	v_exp_f32_e32 v97, v33
	v_exp_f32_e32 v98, v2
	v_exp_f32_e32 v99, v3
	v_exp_f32_e32 v100, v4
	v_exp_f32_e32 v101, v5
	v_exp_f32_e32 v102, v6
	v_exp_f32_e32 v103, v7
	v_exp_f32_e32 v104, v8
	v_exp_f32_e32 v105, v9
	v_exp_f32_e32 v106, v10
	v_exp_f32_e32 v107, v11
	v_exp_f32_e32 v108, v12
	v_exp_f32_e32 v109, v13
	v_exp_f32_e32 v110, v14
	v_exp_f32_e32 v111, v15
	v_exp_f32_e32 v112, v16
	v_exp_f32_e32 v113, v17
	s_xor_b64 s[42:43], s[46:47], -1
	s_add_u32 s46, s40, 0x8000
	v_mov_b32_e32 v216, 0
	v_mov_b32_e32 v240, 0
	v_mov_b32_e32 v241, 0
	v_mov_b32_e32 v242, 0
	v_mov_b32_e32 v243, 0
	v_and_b32_e32 v236, 15, v230
	v_bfe_u32 v237, v230, 4, 1
	v_mov_b32_e32 v238, 0x3f803f80
	v_cmp_eq_u32_e64 s[98:99], v236, v237
	s_nop 1
	v_cndmask_b32_e64 v236, 0, v238, s[98:99]
	v_mov_b32_e32 v237, v236
	v_mov_b32_e32 v238, v236
	v_mov_b32_e32 v239, v236
	s_addc_u32 s47, s41, 0
	s_mov_b32 s14, 1
	s_mov_b32 s9, 0
	s_mov_b32 s67, 4
	s_mov_b64 s[40:41], s[48:49]
	s_mov_b32 s66, s8
	v_mov_b32_e32 v218, v215
	v_mov_b32_e32 v166, v209
	v_mov_b32_e32 v50, 0
	v_mov_b32_e32 v51, v216
	v_mov_b32_e32 v52, v216
	v_mov_b32_e32 v53, v216
	v_mov_b32_e32 v54, v216
	v_mov_b32_e32 v55, v216
	v_mov_b32_e32 v56, v216
	v_mov_b32_e32 v57, v216
	v_mov_b32_e32 v58, v216
	v_mov_b32_e32 v59, v216
	v_mov_b32_e32 v60, v216
	v_mov_b32_e32 v61, v216
	v_mov_b32_e32 v62, v216
	v_mov_b32_e32 v63, v216
	v_mov_b32_e32 v64, v216
	v_mov_b32_e32 v65, v216
	v_mov_b32_e32 v66, 0
	v_mov_b32_e32 v67, v216
	v_mov_b32_e32 v68, v216
	v_mov_b32_e32 v69, v216
	v_mov_b32_e32 v70, v216
	v_mov_b32_e32 v71, v216
	v_mov_b32_e32 v72, v216
	v_mov_b32_e32 v73, v216
	v_mov_b32_e32 v74, v216
	v_mov_b32_e32 v75, v216
	v_mov_b32_e32 v76, v216
	v_mov_b32_e32 v77, v216
	v_mov_b32_e32 v78, v216
	v_mov_b32_e32 v79, v216
	v_mov_b32_e32 v80, v216
	v_mov_b32_e32 v81, v216
	v_mov_b32_e32 v2, 0
	v_mov_b32_e32 v3, v216
	v_mov_b32_e32 v4, v216
	v_mov_b32_e32 v5, v216
	v_mov_b32_e32 v6, v216
	v_mov_b32_e32 v7, v216
	v_mov_b32_e32 v8, v216
	v_mov_b32_e32 v9, v216
	v_mov_b32_e32 v10, v216
	v_mov_b32_e32 v11, v216
	v_mov_b32_e32 v12, v216
	v_mov_b32_e32 v13, v216
	v_mov_b32_e32 v14, v216
	v_mov_b32_e32 v15, v216
	v_mov_b32_e32 v16, v216
	v_mov_b32_e32 v17, v216
	v_mov_b32_e32 v18, 0
	v_mov_b32_e32 v19, v216
	v_mov_b32_e32 v20, v216
	v_mov_b32_e32 v21, v216
	v_mov_b32_e32 v22, v216
	v_mov_b32_e32 v23, v216
	v_mov_b32_e32 v24, v216
	v_mov_b32_e32 v25, v216
	v_mov_b32_e32 v26, v216
	v_mov_b32_e32 v27, v216
	v_mov_b32_e32 v28, v216
	v_mov_b32_e32 v29, v216
	v_mov_b32_e32 v30, v216
	v_mov_b32_e32 v31, v216
	v_mov_b32_e32 v32, v216
	v_mov_b32_e32 v33, v216
	s_branch .LBB0_513
.LBB0_512:
	s_waitcnt lgkmcnt(2)
	v_mfma_f32_32x32x16_bf16 v[50:65], v[162:165], v[122:125], v[50:65]
	ds_read_b64_tr_b16 v[126:127], v222 offset:1024
	ds_read_b64_tr_b16 v[128:129], v222 offset:3072
	v_mfma_f32_16x16x32_bf16 v[240:243], v[114:117], v[236:239], v[240:243]
	v_cndmask_b32_e64 v166, v221, v223, s[4:5]
	v_exp_f32_e32 v98, v98
	v_exp_f32_e32 v99, v99
	s_waitcnt lgkmcnt(2)
	v_mfma_f32_32x32x16_bf16 v[66:81], v[162:165], v[118:121], v[66:81]
	ds_read_b64_tr_b16 v[122:123], v222 offset:1536
	ds_read_b64_tr_b16 v[124:125], v222 offset:3584
	v_exp_f32_e32 v100, v100
	v_exp_f32_e32 v101, v101
	s_waitcnt lgkmcnt(2)
	v_mfma_f32_32x32x16_bf16 v[2:17], v[162:165], v[126:129], v[2:17]
	ds_read_b64_tr_b16 v[118:119], v222 offset:4096
	ds_read_b64_tr_b16 v[120:121], v222 offset:6144
	v_exp_f32_e32 v102, v102
	v_exp_f32_e32 v103, v103
	s_waitcnt lgkmcnt(2)
	v_mfma_f32_32x32x16_bf16 v[18:33], v[162:165], v[122:125], v[18:33]
	ds_read_b64_tr_b16 v[126:127], v222 offset:4608
	ds_read_b64_tr_b16 v[128:129], v222 offset:6656
	v_exp_f32_e32 v104, v104
	v_exp_f32_e32 v105, v105
	s_waitcnt lgkmcnt(2)
	v_mfma_f32_32x32x16_bf16 v[50:65], v[134:137], v[118:121], v[50:65]
	ds_read_b64_tr_b16 v[122:123], v222 offset:5120
	ds_read_b64_tr_b16 v[124:125], v222 offset:7168
	v_exp_f32_e32 v106, v106
	v_exp_f32_e32 v107, v107
	s_waitcnt lgkmcnt(2)
	v_mfma_f32_32x32x16_bf16 v[66:81], v[134:137], v[126:129], v[66:81]
	ds_read_b64_tr_b16 v[118:119], v222 offset:5632
	ds_read_b64_tr_b16 v[120:121], v222 offset:7680
	v_exp_f32_e32 v108, v108
	v_exp_f32_e32 v109, v109
	s_waitcnt lgkmcnt(2)
	v_mfma_f32_32x32x16_bf16 v[2:17], v[134:137], v[122:125], v[2:17]
	ds_read_b64_tr_b16 v[126:127], v222 offset:8192
	ds_read_b64_tr_b16 v[128:129], v222 offset:10240
	v_exp_f32_e32 v110, v110
	v_exp_f32_e32 v111, v111
	s_waitcnt lgkmcnt(2)
	v_mfma_f32_32x32x16_bf16 v[18:33], v[134:137], v[118:121], v[18:33]
	ds_read_b64_tr_b16 v[122:123], v222 offset:8704
	ds_read_b64_tr_b16 v[124:125], v222 offset:10752
	v_exp_f32_e32 v112, v112
	v_exp_f32_e32 v113, v113
	s_waitcnt lgkmcnt(2)
	v_mfma_f32_32x32x16_bf16 v[50:65], v[130:133], v[126:129], v[50:65]
	ds_read_b64_tr_b16 v[118:119], v222 offset:9216
	ds_read_b64_tr_b16 v[120:121], v222 offset:11264
	v_exp_f32_e32 v82, v82
	v_exp_f32_e32 v83, v83
	s_waitcnt lgkmcnt(2)
	v_mfma_f32_32x32x16_bf16 v[66:81], v[130:133], v[122:125], v[66:81]
	ds_read_b64_tr_b16 v[126:127], v222 offset:9728
	ds_read_b64_tr_b16 v[128:129], v222 offset:11776
	v_exp_f32_e32 v84, v84
	v_exp_f32_e32 v85, v85
	s_waitcnt lgkmcnt(2)
	v_mfma_f32_32x32x16_bf16 v[2:17], v[130:133], v[118:121], v[2:17]
	ds_read_b64_tr_b16 v[122:123], v222 offset:12288
	ds_read_b64_tr_b16 v[124:125], v222 offset:14336
	v_exp_f32_e32 v86, v86
	v_exp_f32_e32 v87, v87
	s_waitcnt lgkmcnt(2)
	v_mfma_f32_32x32x16_bf16 v[18:33], v[130:133], v[126:129], v[18:33]
	ds_read_b64_tr_b16 v[118:119], v222 offset:12800
	ds_read_b64_tr_b16 v[120:121], v222 offset:14848
	v_exp_f32_e32 v88, v88
	v_exp_f32_e32 v89, v89
	s_waitcnt lgkmcnt(2)
	v_mfma_f32_32x32x16_bf16 v[50:65], v[114:117], v[122:125], v[50:65]
	ds_read_b64_tr_b16 v[126:127], v222 offset:13312
	ds_read_b64_tr_b16 v[128:129], v222 offset:15360
	v_exp_f32_e32 v90, v90
	v_exp_f32_e32 v91, v91
	s_waitcnt lgkmcnt(2)
	v_mfma_f32_32x32x16_bf16 v[66:81], v[114:117], v[118:121], v[66:81]
	ds_read_b64_tr_b16 v[122:123], v222 offset:13824
	ds_read_b64_tr_b16 v[124:125], v222 offset:15872
	v_exp_f32_e32 v92, v92
	v_exp_f32_e32 v93, v93
	s_waitcnt lgkmcnt(2)
	v_mfma_f32_32x32x16_bf16 v[2:17], v[114:117], v[126:129], v[2:17]
	v_exp_f32_e32 v94, v94
	v_exp_f32_e32 v95, v95
	s_waitcnt lgkmcnt(0)
	v_mfma_f32_32x32x16_bf16 v[18:33], v[114:117], v[122:125], v[18:33]
	v_exp_f32_e32 v96, v96
	v_exp_f32_e32 v97, v97
	s_add_i32 s4, s9, 1
	s_cmp_lg_u32 s9, 4
	s_cselect_b32 s14, s4, 0
	s_add_i32 s67, s67, 2
	s_addk_i32 s66, 0x80
	s_add_u32 s40, s40, 0x8000
	s_waitcnt vmcnt(0) lgkmcnt(0)
	s_barrier
	s_addc_u32 s41, s41, 0
	s_add_u32 s46, s46, 0x4000
	v_add_u32_e32 v218, 0x200, v218
	s_addc_u32 s47, s47, 0
	s_and_b64 vcc, exec, s[50:51]
	s_cbranch_vccnz .LBB0_525

.LBB0_515:
	v_lshl_add_u32 v169, s14, 13, v205
	ds_read_b128 v[114:117], v169
	ds_read_b128 v[220:223], v169 offset:512
	s_lshl_b32 s9, s9, 14
	v_add_u32_e32 v167, s9, v204
	s_waitcnt lgkmcnt(1)
	v_mfma_f32_32x32x16_bf16 v[130:145], v[114:117], v[158:161], v[34:49]
	ds_read_b128 v[224:227], v169 offset:2048
	v_cvt_pk_bf16_f32 v162, v98, v99
	v_cvt_pk_bf16_f32 v163, v100, v101
	ds_read_b128 v[98:101], v169 offset:2560
	v_cvt_pk_bf16_f32 v164, v102, v103
	s_waitcnt lgkmcnt(2)
	v_mfma_f32_32x32x16_bf16 v[114:129], v[220:223], v[158:161], v[34:49]
	v_cvt_pk_bf16_f32 v165, v104, v105
	s_waitcnt lgkmcnt(1)
	v_mfma_f32_32x32x16_bf16 v[130:145], v[224:227], v[154:157], v[130:145]
	ds_read_b128 v[220:223], v169 offset:4096
	v_mfma_f32_16x16x32_bf16 v[240:243], v[162:165], v[236:239], v[240:243]
	v_cvt_pk_bf16_f32 v102, v106, v107
	v_cvt_pk_bf16_f32 v103, v108, v109
	s_waitcnt lgkmcnt(1)
	v_mfma_f32_32x32x16_bf16 v[114:129], v[98:101], v[154:157], v[114:129]
	ds_read_b128 v[106:109], v169 offset:4608
	v_cvt_pk_bf16_f32 v104, v110, v111
	v_cvt_pk_bf16_f32 v105, v112, v113
	s_waitcnt lgkmcnt(1)
	v_mfma_f32_32x32x16_bf16 v[130:145], v[220:223], v[150:153], v[130:145]
	ds_read_b128 v[110:113], v169 offset:6144
	v_mfma_f32_16x16x32_bf16 v[240:243], v[102:105], v[236:239], v[240:243]
	v_cvt_pk_bf16_f32 v98, v82, v83
	v_cvt_pk_bf16_f32 v99, v84, v85
	s_waitcnt lgkmcnt(1)
	v_mfma_f32_32x32x16_bf16 v[114:129], v[106:109], v[150:153], v[114:129]
	ds_read_b128 v[220:223], v169 offset:6656
	v_cvt_pk_bf16_f32 v100, v86, v87
	v_cvt_pk_bf16_f32 v101, v88, v89
	s_waitcnt lgkmcnt(1)
	v_mfma_f32_32x32x16_bf16 v[130:145], v[110:113], v[146:149], v[130:145]
	v_cvt_pk_bf16_f32 v82, v90, v91
	v_mfma_f32_16x16x32_bf16 v[240:243], v[98:101], v[236:239], v[240:243]
	v_cvt_pk_bf16_f32 v83, v92, v93
	ds_read_b64_tr_b16 v[86:87], v167
	ds_read_b64_tr_b16 v[88:89], v167 offset:2048
	s_waitcnt lgkmcnt(2)
	v_mfma_f32_32x32x16_bf16 v[114:129], v[220:223], v[146:149], v[114:129]
	v_cvt_pk_bf16_f32 v84, v94, v95
	v_cvt_pk_bf16_f32 v85, v96, v97
	ds_read_b64_tr_b16 v[90:91], v167 offset:512
	ds_read_b64_tr_b16 v[92:93], v167 offset:2560
	s_add_i32 s9, s67, -1
	s_cmp_ge_u32 s9, s55
	s_cbranch_scc0 .LBB0_523
	s_cmp_ge_u32 s67, s55
	s_cselect_b64 s[50:51], -1, 0
	s_and_b64 vcc, exec, s[50:51]
	s_cbranch_vccz .LBB0_524

.LBB0_519:
	s_waitcnt lgkmcnt(2)
	v_mfma_f32_32x32x16_bf16 v[50:65], v[162:165], v[86:89], v[50:65]
	ds_read_b64_tr_b16 v[94:95], v167 offset:1024
	ds_read_b64_tr_b16 v[96:97], v167 offset:3072
	v_mfma_f32_16x16x32_bf16 v[240:243], v[82:85], v[236:239], v[240:243]
	v_exp_f32_e32 v130, v130
	v_exp_f32_e32 v131, v131
	v_cndmask_b32_e64 v221, v166, v168, s[4:5]
	s_waitcnt lgkmcnt(2)
	v_mfma_f32_32x32x16_bf16 v[66:81], v[162:165], v[90:93], v[66:81]
	ds_read_b64_tr_b16 v[86:87], v167 offset:1536
	ds_read_b64_tr_b16 v[88:89], v167 offset:3584
	v_exp_f32_e32 v132, v132
	v_exp_f32_e32 v133, v133
	s_waitcnt lgkmcnt(2)
	v_mfma_f32_32x32x16_bf16 v[2:17], v[162:165], v[94:97], v[2:17]
	ds_read_b64_tr_b16 v[90:91], v167 offset:4096
	ds_read_b64_tr_b16 v[92:93], v167 offset:6144
	v_exp_f32_e32 v134, v134
	v_exp_f32_e32 v135, v135
	s_waitcnt lgkmcnt(2)
	v_mfma_f32_32x32x16_bf16 v[18:33], v[162:165], v[86:89], v[18:33]
	ds_read_b64_tr_b16 v[94:95], v167 offset:4608
	ds_read_b64_tr_b16 v[96:97], v167 offset:6656
	v_exp_f32_e32 v136, v136
	v_exp_f32_e32 v137, v137
	s_waitcnt lgkmcnt(2)
	v_mfma_f32_32x32x16_bf16 v[50:65], v[102:105], v[90:93], v[50:65]
	ds_read_b64_tr_b16 v[86:87], v167 offset:5120
	ds_read_b64_tr_b16 v[88:89], v167 offset:7168
	v_exp_f32_e32 v138, v138
	v_exp_f32_e32 v139, v139
	s_waitcnt lgkmcnt(2)
	v_mfma_f32_32x32x16_bf16 v[66:81], v[102:105], v[94:97], v[66:81]
	ds_read_b64_tr_b16 v[90:91], v167 offset:5632
	ds_read_b64_tr_b16 v[92:93], v167 offset:7680
	v_exp_f32_e32 v140, v140
	v_exp_f32_e32 v141, v141
	s_waitcnt lgkmcnt(2)
	v_mfma_f32_32x32x16_bf16 v[2:17], v[102:105], v[86:89], v[2:17]
	ds_read_b64_tr_b16 v[94:95], v167 offset:8192
	ds_read_b64_tr_b16 v[96:97], v167 offset:10240
	v_exp_f32_e32 v142, v142
	v_exp_f32_e32 v143, v143
	s_waitcnt lgkmcnt(2)
	v_mfma_f32_32x32x16_bf16 v[18:33], v[102:105], v[90:93], v[18:33]
	ds_read_b64_tr_b16 v[86:87], v167 offset:8704
	ds_read_b64_tr_b16 v[88:89], v167 offset:10752
	v_exp_f32_e32 v144, v144
	v_exp_f32_e32 v145, v145
	s_waitcnt lgkmcnt(2)
	v_mfma_f32_32x32x16_bf16 v[50:65], v[98:101], v[94:97], v[50:65]
	ds_read_b64_tr_b16 v[90:91], v167 offset:9216
	ds_read_b64_tr_b16 v[92:93], v167 offset:11264
	v_exp_f32_e32 v114, v114
	v_exp_f32_e32 v115, v115
	s_waitcnt lgkmcnt(2)
	v_mfma_f32_32x32x16_bf16 v[66:81], v[98:101], v[86:89], v[66:81]
	ds_read_b64_tr_b16 v[94:95], v167 offset:9728
	ds_read_b64_tr_b16 v[96:97], v167 offset:11776
	v_exp_f32_e32 v116, v116
	v_exp_f32_e32 v117, v117
	s_waitcnt lgkmcnt(2)
	v_mfma_f32_32x32x16_bf16 v[2:17], v[98:101], v[90:93], v[2:17]
	ds_read_b64_tr_b16 v[86:87], v167 offset:12288
	ds_read_b64_tr_b16 v[88:89], v167 offset:14336
	v_exp_f32_e32 v118, v118
	v_exp_f32_e32 v119, v119
	s_waitcnt lgkmcnt(2)
	v_mfma_f32_32x32x16_bf16 v[18:33], v[98:101], v[94:97], v[18:33]
	ds_read_b64_tr_b16 v[90:91], v167 offset:12800
	ds_read_b64_tr_b16 v[92:93], v167 offset:14848
	v_exp_f32_e32 v120, v120
	v_exp_f32_e32 v121, v121
	s_waitcnt lgkmcnt(2)
	v_mfma_f32_32x32x16_bf16 v[50:65], v[82:85], v[86:89], v[50:65]
	ds_read_b64_tr_b16 v[94:95], v167 offset:13312
	ds_read_b64_tr_b16 v[96:97], v167 offset:15360
	v_exp_f32_e32 v122, v122
	v_exp_f32_e32 v123, v123
	s_waitcnt lgkmcnt(2)
	v_mfma_f32_32x32x16_bf16 v[66:81], v[82:85], v[90:93], v[66:81]
	ds_read_b64_tr_b16 v[86:87], v167 offset:13824
	ds_read_b64_tr_b16 v[88:89], v167 offset:15872
	v_exp_f32_e32 v124, v124
	v_exp_f32_e32 v125, v125
	s_waitcnt lgkmcnt(2)
	v_mfma_f32_32x32x16_bf16 v[2:17], v[82:85], v[94:97], v[2:17]
	v_exp_f32_e32 v126, v126
	v_exp_f32_e32 v127, v127
	s_waitcnt lgkmcnt(0)
	v_mfma_f32_32x32x16_bf16 v[18:33], v[82:85], v[86:89], v[18:33]
	v_exp_f32_e32 v128, v128
	v_exp_f32_e32 v129, v129
	s_add_i32 s4, s14, -4
	s_add_i32 s9, s14, 1
	s_cmp_gt_i32 s14, 3
	s_cselect_b32 s4, s4, s9
	v_lshl_add_u32 v86, s4, 13, v205
	s_add_i32 s4, s66, 0xffffff42
	s_cmpk_lt_i32 s4, 0xff42
	s_cselect_b64 vcc, -1, 0
	s_cmpk_gt_i32 s4, 0x9e
	ds_read_b128 v[82:85], v86
	ds_read_b128 v[166:169], v86 offset:512
	s_cselect_b64 s[4:5], -1, 0
	v_cndmask_b32_e64 v86, 0, v207, s[4:5]
	v_cndmask_b32_e32 v223, v86, v206, vcc
	v_cmp_eq_f32_e32 vcc, v223, v221
	v_cmp_neq_f32_e64 s[4:5], v223, v221
	s_cbranch_vccnz .LBB0_521
	v_sub_f32_e32 v34, v223, v217
	v_mov_b32_e32 v35, v34
	v_mov_b32_e32 v36, v34
	v_mov_b32_e32 v37, v34
	v_mov_b32_e32 v38, v34
	v_mov_b32_e32 v39, v34
	v_mov_b32_e32 v40, v34
	v_mov_b32_e32 v41, v34
	v_mov_b32_e32 v42, v34
	v_mov_b32_e32 v43, v34
	v_mov_b32_e32 v44, v34
	v_mov_b32_e32 v45, v34
	v_mov_b32_e32 v46, v34
	v_mov_b32_e32 v47, v34
	v_mov_b32_e32 v48, v34
	v_mov_b32_e32 v49, v34
; #define LAS __attribute__((address_space(3)))
; #define SBAR() __builtin_amdgcn_sched_barrier(0)
; #define SBAR() __builtin_amdgcn_sched_barrier(0)
; template <bool BIAS>
; __device__ __forceinline__ void bias_add(f32x16& p0, f32x16& p1, int bmode, const LAS float* tab, int idx0) {
;     if constexpr (BIAS) {
;         if (bmode == 2) {
; #pragma unroll
;             for (int r = 0; r < 16; ++r) { const int o = (r & 3) + 8 * (r >> 2); p0[r] += tab[idx0 + o]; p1[r] += tab[idx0 + 32 + o]; if ((r & 3) == 3) { asm volatile("" : "+v"(p0), "+v"(p1)); SBAR(); } }
;         }
;     }
.LBB0_521:
	s_cmp_lg_u32 s14, 4
	s_cselect_b32 s9, s9, 0
	s_lshl_b32 s12, s14, 14
	s_cmpk_gt_u32 s66, 0x15c
	v_add_u32_e32 v222, s12, v204
	v_lshl_add_u32 v228, s9, 13, v205
	s_waitcnt lgkmcnt(1)
	v_mfma_f32_32x32x16_bf16 v[98:113], v[82:85], v[158:161], v[34:49]
	ds_read_b128 v[224:227], v228 offset:2048
	v_cvt_pk_bf16_f32 v162, v130, v131
	v_cvt_pk_bf16_f32 v163, v132, v133
	s_nop 0
	ds_read_b128 v[130:133], v228 offset:2560
	v_cvt_pk_bf16_f32 v164, v134, v135
	v_cvt_pk_bf16_f32 v165, v136, v137
	s_waitcnt lgkmcnt(2)
	v_mfma_f32_32x32x16_bf16 v[82:97], v[166:169], v[158:161], v[34:49]
	s_waitcnt lgkmcnt(1)
	v_mfma_f32_32x32x16_bf16 v[98:113], v[224:227], v[154:157], v[98:113]
	ds_read_b128 v[166:169], v228 offset:4096
	v_mfma_f32_16x16x32_bf16 v[240:243], v[162:165], v[236:239], v[240:243]
	v_cvt_pk_bf16_f32 v134, v138, v139
	v_cvt_pk_bf16_f32 v135, v140, v141
	s_waitcnt lgkmcnt(1)
	v_mfma_f32_32x32x16_bf16 v[82:97], v[130:133], v[154:157], v[82:97]
	ds_read_b128 v[138:141], v228 offset:4608
	v_cvt_pk_bf16_f32 v136, v142, v143
	v_cvt_pk_bf16_f32 v137, v144, v145
	s_waitcnt lgkmcnt(1)
	v_mfma_f32_32x32x16_bf16 v[98:113], v[166:169], v[150:153], v[98:113]
	ds_read_b128 v[142:145], v228 offset:6144
	v_mfma_f32_16x16x32_bf16 v[240:243], v[134:137], v[236:239], v[240:243]
	v_cvt_pk_bf16_f32 v130, v114, v115
	v_cvt_pk_bf16_f32 v131, v116, v117
	s_waitcnt lgkmcnt(1)
	v_mfma_f32_32x32x16_bf16 v[82:97], v[138:141], v[150:153], v[82:97]
	ds_read_b128 v[166:169], v228 offset:6656
	v_cvt_pk_bf16_f32 v132, v118, v119
	v_cvt_pk_bf16_f32 v133, v120, v121
	s_waitcnt lgkmcnt(1)
	v_mfma_f32_32x32x16_bf16 v[98:113], v[142:145], v[146:149], v[98:113]
	v_cvt_pk_bf16_f32 v114, v122, v123
	v_mfma_f32_16x16x32_bf16 v[240:243], v[130:133], v[236:239], v[240:243]
	v_cvt_pk_bf16_f32 v115, v124, v125
	ds_read_b64_tr_b16 v[122:123], v222
	ds_read_b64_tr_b16 v[124:125], v222 offset:2048
	s_waitcnt lgkmcnt(2)
	v_mfma_f32_32x32x16_bf16 v[82:97], v[166:169], v[146:149], v[82:97]
	v_cvt_pk_bf16_f32 v116, v126, v127
	v_cvt_pk_bf16_f32 v117, v128, v129
	ds_read_b64_tr_b16 v[118:119], v222 offset:512
	ds_read_b64_tr_b16 v[120:121], v222 offset:2560
	s_cbranch_scc1 .LBB0_512
	ds_read2_b32 v[128:129], v218 offset0:64 offset1:65
	s_waitcnt lgkmcnt(0)
	v_pk_add_f32 v[98:99], v[98:99], v[128:129]
	ds_read2_b32 v[128:129], v218 offset0:96 offset1:97
	s_waitcnt lgkmcnt(0)
	v_pk_add_f32 v[82:83], v[82:83], v[128:129]
	ds_read2_b32 v[128:129], v218 offset0:66 offset1:67
	s_waitcnt lgkmcnt(0)
	v_pk_add_f32 v[100:101], v[100:101], v[128:129]
	ds_read2_b32 v[128:129], v218 offset0:98 offset1:99
	s_waitcnt lgkmcnt(0)
	v_pk_add_f32 v[84:85], v[84:85], v[128:129]
	s_nop 0
	ds_read2_b32 v[128:129], v218 offset0:72 offset1:73
	s_waitcnt lgkmcnt(0)
	v_pk_add_f32 v[102:103], v[128:129], v[102:103]
	ds_read2_b32 v[128:129], v218 offset0:104 offset1:105
	s_waitcnt lgkmcnt(0)
	v_pk_add_f32 v[86:87], v[86:87], v[128:129]
	ds_read2_b32 v[128:129], v218 offset0:74 offset1:75
	s_waitcnt lgkmcnt(0)
	v_pk_add_f32 v[104:105], v[104:105], v[128:129]
	ds_read2_b32 v[128:129], v218 offset0:106 offset1:107
	s_waitcnt lgkmcnt(0)
	v_pk_add_f32 v[88:89], v[88:89], v[128:129]
	s_nop 0
	ds_read2_b32 v[128:129], v218 offset0:80 offset1:81
	s_waitcnt lgkmcnt(0)
	v_pk_add_f32 v[106:107], v[128:129], v[106:107]
	ds_read2_b32 v[128:129], v218 offset0:112 offset1:113
	s_waitcnt lgkmcnt(0)
	v_pk_add_f32 v[90:91], v[90:91], v[128:129]
	ds_read2_b32 v[128:129], v218 offset0:82 offset1:83
	s_waitcnt lgkmcnt(0)
	v_pk_add_f32 v[108:109], v[108:109], v[128:129]
	ds_read2_b32 v[128:129], v218 offset0:114 offset1:115
	s_waitcnt lgkmcnt(0)
	v_pk_add_f32 v[92:93], v[92:93], v[128:129]
	s_nop 0
	ds_read2_b32 v[128:129], v218 offset0:88 offset1:89
	s_waitcnt lgkmcnt(0)
	v_pk_add_f32 v[110:111], v[128:129], v[110:111]
	ds_read2_b32 v[128:129], v218 offset0:120 offset1:121
	s_waitcnt lgkmcnt(0)
	v_pk_add_f32 v[94:95], v[94:95], v[128:129]
	ds_read2_b32 v[128:129], v218 offset0:90 offset1:91
	s_waitcnt lgkmcnt(0)
	v_pk_add_f32 v[112:113], v[112:113], v[128:129]
	ds_read2_b32 v[128:129], v218 offset0:122 offset1:123
	s_waitcnt lgkmcnt(0)
	v_pk_add_f32 v[96:97], v[96:97], v[128:129]
	s_nop 0
	s_branch .LBB0_512

; #define LAS __attribute__((address_space(3)))
; #define PKW(P, B) cvtpk(P[B], P[B + 1])
; #define MFMA32(a, b, c) __builtin_amdgcn_mfma_f32_32x32x16_bf16(a, b, c, 0, 0, 0)
; #define VRD(g) do { const int o_ = ((g) % NCB) * 512 + (2 * ((g) / NCB)) * NCB * 512; vl[(g) % 3] = tr_rd(vp_ + o_); vh[(g) % 3] = tr_rd(vp_ + o_ + NCB * 512); } while (0)
; template <int NCB, bool DIFF, bool STAT>
; __device__ __forceinline__ void attn_unit(LAS char* lds, const Params& P, int s, int head, int qb, float sref) {
;     ...
;         for (int j = 1; j + 1 < NT; j += 2) {
;             STEP(pB0, pB1, alB, pA0, pA1, alA, j, false, false);
;             STEP(pA0, pA1, alA, pB0, pB1, alB, j + 1, true, true);
;         }
;         STEP(pB0, pB1, alB, pA0, pA1, alA, NT - 1, false, false);
;         { const LAS char* vp_ = vp0 + sl_prev * SHM_V; s16x4 vl[3], vh[3];
;           float s0_ = 0.f;
; #pragma unroll
;           for (int r = 0; r < 16; ++r) s0_ += pB0[r] + pB1[r];
;           if constexpr (STAT) l_reg += s0_; else l_reg = l_reg * alB + s0_;
;           pw[0] = (u32x4){PKW(pB0, 0), PKW(pB0, 2), PKW(pB0, 4), PKW(pB0, 6)}; pw[1] = (u32x4){PKW(pB0, 8), PKW(pB0, 10), PKW(pB0, 12), PKW(pB0, 14)};
;           pw[2] = (u32x4){PKW(pB1, 0), PKW(pB1, 2), PKW(pB1, 4), PKW(pB1, 6)}; pw[3] = (u32x4){PKW(pB1, 8), PKW(pB1, 10), PKW(pB1, 12), PKW(pB1, 14)};
; #pragma unroll
;           for (int g = 0; g < NG; ++g) { VRD(g); o[g % NCB] = MFMA32(__builtin_bit_cast(bf16x8, pw[g / NCB]), PKV(vl[g % 3], vh[g % 3]), o[g % NCB]); } }
.LBB0_529:
	s_waitcnt lgkmcnt(2)
	v_mfma_f32_32x32x16_bf16 v[50:65], v[130:133], v[90:93], v[50:65]
	ds_read_b64_tr_b16 v[106:107], v134 offset:1024
	ds_read_b64_tr_b16 v[108:109], v134 offset:3072
	v_add_f32_e32 v94, v94, v95
	v_exp_f32_e32 v114, v114
	v_exp_f32_e32 v115, v115
	v_add_f32_e32 v94, v216, v94
	s_waitcnt lgkmcnt(2)
	v_mfma_f32_32x32x16_bf16 v[66:81], v[130:133], v[86:89], v[66:81]
	ds_read_b64_tr_b16 v[90:91], v134 offset:1536
	ds_read_b64_tr_b16 v[92:93], v134 offset:3584
	v_exp_f32_e32 v116, v116
	v_exp_f32_e32 v117, v117
	s_waitcnt lgkmcnt(2)
	v_mfma_f32_32x32x16_bf16 v[2:17], v[130:133], v[106:109], v[2:17]
	ds_read_b64_tr_b16 v[86:87], v134 offset:4096
	ds_read_b64_tr_b16 v[88:89], v134 offset:6144
	v_exp_f32_e32 v118, v118
	v_exp_f32_e32 v119, v119
	s_waitcnt lgkmcnt(2)
	v_mfma_f32_32x32x16_bf16 v[18:33], v[130:133], v[90:93], v[18:33]
	ds_read_b64_tr_b16 v[106:107], v134 offset:4608
	ds_read_b64_tr_b16 v[108:109], v134 offset:6656
	v_exp_f32_e32 v120, v120
	v_exp_f32_e32 v121, v121
	s_waitcnt lgkmcnt(2)
	v_mfma_f32_32x32x16_bf16 v[50:65], v[102:105], v[86:89], v[50:65]
	ds_read_b64_tr_b16 v[90:91], v134 offset:5120
	ds_read_b64_tr_b16 v[92:93], v134 offset:7168
	v_exp_f32_e32 v122, v122
	v_exp_f32_e32 v123, v123
	s_waitcnt lgkmcnt(2)
	v_mfma_f32_32x32x16_bf16 v[66:81], v[102:105], v[106:109], v[66:81]
	ds_read_b64_tr_b16 v[86:87], v134 offset:5632
	ds_read_b64_tr_b16 v[88:89], v134 offset:7680
	v_exp_f32_e32 v124, v124
	v_exp_f32_e32 v125, v125
	s_waitcnt lgkmcnt(2)
	v_mfma_f32_32x32x16_bf16 v[2:17], v[102:105], v[90:93], v[2:17]
	ds_read_b64_tr_b16 v[106:107], v134 offset:8192
	ds_read_b64_tr_b16 v[108:109], v134 offset:10240
	v_exp_f32_e32 v126, v126
	v_exp_f32_e32 v127, v127
	s_waitcnt lgkmcnt(2)
	v_mfma_f32_32x32x16_bf16 v[18:33], v[102:105], v[86:89], v[18:33]
	ds_read_b64_tr_b16 v[90:91], v134 offset:8704
	ds_read_b64_tr_b16 v[92:93], v134 offset:10752
	v_exp_f32_e32 v128, v128
	v_exp_f32_e32 v129, v129
	s_waitcnt lgkmcnt(2)
	v_mfma_f32_32x32x16_bf16 v[50:65], v[98:101], v[106:109], v[50:65]
	ds_read_b64_tr_b16 v[86:87], v134 offset:9216
	ds_read_b64_tr_b16 v[88:89], v134 offset:11264
	v_exp_f32_e32 v34, v34
	v_exp_f32_e32 v35, v35
	s_waitcnt lgkmcnt(2)
	v_mfma_f32_32x32x16_bf16 v[66:81], v[98:101], v[90:93], v[66:81]
	ds_read_b64_tr_b16 v[102:103], v134 offset:9728
	ds_read_b64_tr_b16 v[104:105], v134 offset:11776
	v_exp_f32_e32 v36, v36
	v_exp_f32_e32 v37, v37
	s_waitcnt lgkmcnt(2)
	v_mfma_f32_32x32x16_bf16 v[2:17], v[98:101], v[86:89], v[2:17]
	ds_read_b64_tr_b16 v[90:91], v134 offset:12288
	ds_read_b64_tr_b16 v[92:93], v134 offset:14336
	v_exp_f32_e32 v38, v38
	v_exp_f32_e32 v39, v39
	s_waitcnt lgkmcnt(2)
	v_mfma_f32_32x32x16_bf16 v[18:33], v[98:101], v[102:105], v[18:33]
	ds_read_b64_tr_b16 v[86:87], v134 offset:12800
	ds_read_b64_tr_b16 v[88:89], v134 offset:14848
	v_exp_f32_e32 v40, v40
	v_exp_f32_e32 v41, v41
	s_waitcnt lgkmcnt(2)
	v_mfma_f32_32x32x16_bf16 v[50:65], v[82:85], v[90:93], v[50:65]
	ds_read_b64_tr_b16 v[96:97], v134 offset:13312
	ds_read_b64_tr_b16 v[98:99], v134 offset:15360
	v_exp_f32_e32 v42, v42
	v_exp_f32_e32 v43, v43
	s_waitcnt lgkmcnt(2)
	v_mfma_f32_32x32x16_bf16 v[66:81], v[82:85], v[86:89], v[66:81]
	ds_read_b64_tr_b16 v[90:91], v134 offset:13824
	ds_read_b64_tr_b16 v[92:93], v134 offset:15872
	v_exp_f32_e32 v44, v44
	v_exp_f32_e32 v45, v45
	s_waitcnt lgkmcnt(2)
	v_mfma_f32_32x32x16_bf16 v[2:17], v[82:85], v[96:99], v[2:17]
	v_exp_f32_e32 v46, v46
	v_exp_f32_e32 v47, v47
	s_waitcnt lgkmcnt(0)
	v_mfma_f32_32x32x16_bf16 v[18:33], v[82:85], v[90:93], v[18:33]
	v_exp_f32_e32 v48, v48
	v_exp_f32_e32 v49, v49
	v_lshl_add_u32 v111, s14, 14, v204
	v_add_f32_e32 v95, v114, v34
	v_add_f32_e32 v96, v115, v35
	v_add_f32_e32 v97, v116, v36
	v_add_f32_e32 v98, v117, v37
	v_add_f32_e32 v99, v118, v38
	v_add_f32_e32 v100, v119, v39
	v_add_f32_e32 v101, v120, v40
	v_add_f32_e32 v102, v121, v41
	v_cvt_pk_bf16_f32 v82, v114, v115
	v_cvt_pk_bf16_f32 v83, v116, v117
	v_cvt_pk_bf16_f32 v84, v118, v119
	v_cvt_pk_bf16_f32 v85, v120, v121
	v_cvt_pk_bf16_f32 v86, v122, v123
	v_cvt_pk_bf16_f32 v87, v124, v125
	v_cvt_pk_bf16_f32 v88, v126, v127
	v_cvt_pk_bf16_f32 v89, v128, v129
	v_cvt_pk_bf16_f32 v90, v34, v35
	v_cvt_pk_bf16_f32 v91, v36, v37
	v_cvt_pk_bf16_f32 v92, v38, v39
	v_cvt_pk_bf16_f32 v93, v40, v41
	v_cvt_pk_bf16_f32 v34, v42, v43
	v_cvt_pk_bf16_f32 v35, v44, v45
	v_cvt_pk_bf16_f32 v36, v46, v47
	v_cvt_pk_bf16_f32 v37, v48, v49
	ds_read_b64_tr_b16 v[38:39], v111
	ds_read_b64_tr_b16 v[40:41], v111 offset:2048
	s_waitcnt lgkmcnt(0)
	v_mfma_f32_32x32x16_bf16 v[50:65], v[82:85], v[38:41], v[50:65]
	ds_read_b64_tr_b16 v[38:39], v111 offset:512
	ds_read_b64_tr_b16 v[40:41], v111 offset:2560
	v_add_f32_e32 v103, v122, v42
	v_add_f32_e32 v104, v123, v43
	v_add_f32_e32 v105, v124, v44
	v_add_f32_e32 v106, v125, v45
	v_add_f32_e32 v107, v126, v46
	v_add_f32_e32 v108, v127, v47
	s_waitcnt lgkmcnt(0)
	v_mfma_f32_32x32x16_bf16 v[66:81], v[82:85], v[38:41], v[66:81]
	ds_read_b64_tr_b16 v[38:39], v111 offset:1024
	ds_read_b64_tr_b16 v[40:41], v111 offset:3072
	v_add_f32_e32 v109, v128, v48
	v_add_f32_e32 v110, v129, v49
	s_waitcnt lgkmcnt(0)
	v_mfma_f32_32x32x16_bf16 v[2:17], v[82:85], v[38:41], v[2:17]
	ds_read_b64_tr_b16 v[38:39], v111 offset:1536
	ds_read_b64_tr_b16 v[40:41], v111 offset:3584
	s_waitcnt lgkmcnt(0)
	v_mfma_f32_32x32x16_bf16 v[18:33], v[82:85], v[38:41], v[18:33]
	ds_read_b64_tr_b16 v[38:39], v111 offset:4096
	ds_read_b64_tr_b16 v[40:41], v111 offset:6144
	s_waitcnt lgkmcnt(0)
	v_mfma_f32_32x32x16_bf16 v[50:65], v[86:89], v[38:41], v[50:65]
	ds_read_b64_tr_b16 v[38:39], v111 offset:4608
	ds_read_b64_tr_b16 v[40:41], v111 offset:6656
	s_waitcnt lgkmcnt(0)
; __device__ __forceinline__ int crow(int r, int hi) { return (r & 3) + 8 * (r >> 2) + 4 * hi; }
; __device__ __forceinline__ int crow(int r, int hi) { return (r & 3) + 8 * (r >> 2) + 4 * hi; }
; #define PKW(P, B) cvtpk(P[B], P[B + 1])
; #define MFMA32(a, b, c) __builtin_amdgcn_mfma_f32_32x32x16_bf16(a, b, c, 0, 0, 0)
; #define VRD(g) do { const int o_ = ((g) % NCB) * 512 + (2 * ((g) / NCB)) * NCB * 512; vl[(g) % 3] = tr_rd(vp_ + o_); vh[(g) % 3] = tr_rd(vp_ + o_ + NCB * 512); } while (0)
; template <int NCB, bool DIFF, bool STAT>
; __device__ __forceinline__ void attn_unit(LAS char* lds, const Params& P, int s, int head, int qb, float sref) {
;     ...
;           for (int r = 0; r < 16; ++r) s0_ += pB0[r] + pB1[r];
;           if constexpr (STAT) l_reg += s0_; else l_reg = l_reg * alB + s0_;
;           pw[0] = (u32x4){PKW(pB0, 0), PKW(pB0, 2), PKW(pB0, 4), PKW(pB0, 6)}; pw[1] = (u32x4){PKW(pB0, 8), PKW(pB0, 10), PKW(pB0, 12), PKW(pB0, 14)};
;           pw[2] = (u32x4){PKW(pB1, 0), PKW(pB1, 2), PKW(pB1, 4), PKW(pB1, 6)}; pw[3] = (u32x4){PKW(pB1, 8), PKW(pB1, 10), PKW(pB1, 12), PKW(pB1, 14)};
; #pragma unroll
;           for (int g = 0; g < NG; ++g) { VRD(g); o[g % NCB] = MFMA32(__builtin_bit_cast(bf16x8, pw[g / NCB]), PKV(vl[g % 3], vh[g % 3]), o[g % NCB]); } }
;     ...
;         { auto rr = __builtin_amdgcn_permlane32_swap(__float_as_uint(l_reg), __float_as_uint(l_reg), false, false); l_reg = __uint_as_float(rr[0]) + __uint_as_float(rr[1]); }
;         if (hi == 0) li_l[r32] = l_reg; asm volatile("s_waitcnt lgkmcnt(0)" ::: "memory");
;         float rli[16];
; #pragma unroll
;         for (int r = 0; r < 16; ++r) rli[r] = __builtin_amdgcn_rcpf(li_l[crow(r, hi)]);
	v_mfma_f32_32x32x16_bf16 v[66:81], v[86:89], v[38:41], v[66:81]
	ds_read_b64_tr_b16 v[38:39], v111 offset:5120
	ds_read_b64_tr_b16 v[40:41], v111 offset:7168
	s_waitcnt lgkmcnt(0)
	v_mfma_f32_32x32x16_bf16 v[2:17], v[86:89], v[38:41], v[2:17]
	ds_read_b64_tr_b16 v[38:39], v111 offset:5632
	ds_read_b64_tr_b16 v[40:41], v111 offset:7680
	s_waitcnt lgkmcnt(0)
	v_mfma_f32_32x32x16_bf16 v[18:33], v[86:89], v[38:41], v[18:33]
	ds_read_b64_tr_b16 v[38:39], v111 offset:8192
	ds_read_b64_tr_b16 v[40:41], v111 offset:10240
	s_waitcnt lgkmcnt(0)
	v_mfma_f32_32x32x16_bf16 v[50:65], v[90:93], v[38:41], v[50:65]
	ds_read_b64_tr_b16 v[38:39], v111 offset:8704
	ds_read_b64_tr_b16 v[40:41], v111 offset:10752
	s_waitcnt lgkmcnt(0)
	v_mfma_f32_32x32x16_bf16 v[66:81], v[90:93], v[38:41], v[66:81]
	ds_read_b64_tr_b16 v[38:39], v111 offset:9216
	ds_read_b64_tr_b16 v[40:41], v111 offset:11264
	s_waitcnt lgkmcnt(0)
	v_mfma_f32_32x32x16_bf16 v[2:17], v[90:93], v[38:41], v[2:17]
	ds_read_b64_tr_b16 v[38:39], v111 offset:9728
	ds_read_b64_tr_b16 v[40:41], v111 offset:11776
	s_waitcnt lgkmcnt(0)
	v_mfma_f32_32x32x16_bf16 v[18:33], v[90:93], v[38:41], v[18:33]
	ds_read_b64_tr_b16 v[38:39], v111 offset:12288
	ds_read_b64_tr_b16 v[40:41], v111 offset:14336
	s_waitcnt lgkmcnt(0)
	v_mfma_f32_32x32x16_bf16 v[50:65], v[34:37], v[38:41], v[50:65]
	ds_read_b64_tr_b16 v[38:39], v111 offset:12800
	ds_read_b64_tr_b16 v[40:41], v111 offset:14848
	s_waitcnt lgkmcnt(0)
	v_mfma_f32_32x32x16_bf16 v[66:81], v[34:37], v[38:41], v[66:81]
	ds_read_b64_tr_b16 v[38:39], v111 offset:13312
	ds_read_b64_tr_b16 v[40:41], v111 offset:15360
	s_waitcnt lgkmcnt(0)
	v_mfma_f32_32x32x16_bf16 v[2:17], v[34:37], v[38:41], v[2:17]
	ds_read_b64_tr_b16 v[38:39], v111 offset:13824
	ds_read_b64_tr_b16 v[40:41], v111 offset:15872
	s_waitcnt lgkmcnt(0)
	v_mfma_f32_32x32x16_bf16 v[18:33], v[34:37], v[38:41], v[18:33]
	v_add_f32_e32 v34, 0, v95
	v_add_f32_e32 v34, v96, v34
	v_add_f32_e32 v34, v97, v34
	v_add_f32_e32 v34, v98, v34
	v_add_f32_e32 v34, v99, v34
	v_add_f32_e32 v34, v100, v34
	v_add_f32_e32 v34, v101, v34
	v_add_f32_e32 v34, v102, v34
	v_add_f32_e32 v34, v103, v34
	v_add_f32_e32 v34, v104, v34
	v_add_f32_e32 v34, v105, v34
	v_add_f32_e32 v34, v106, v34
	v_add_f32_e32 v34, v107, v34
	v_add_f32_e32 v34, v108, v34
	v_add_f32_e32 v34, v109, v34
	v_add_f32_e32 v34, v110, v34
	v_add_f32_e32 v34, v94, v34
	v_mov_b32_e32 v35, v34
	s_nop 1
	v_permlane32_swap_b32_e32 v34, v35
	s_and_saveexec_b64 s[4:5], s[6:7]
	v_add_f32_e32 v34, v34, v35
	ds_write_b32 v213, v34
	s_or_b64 exec, exec, s[4:5]
	v_and_b32_e32 v34, 31, v230
	v_and_b32_e32 v35, 1, v230
	v_bfe_u32 v36, v230, 4, 2
	v_and_b32_e32 v37, 14, v230
	v_lshlrev_b32_e32 v34, 2, v34
	v_lshlrev_b32_e32 v35, 6, v35
	v_sub_u32_e32 v34, v213, v34
	v_lshl_add_u32 v35, v36, 4, v35
	v_cmp_eq_u32_e64 s[98:99], 0, v37
	v_add_u32_e32 v34, v34, v35
	s_and_saveexec_b64 s[100:101], s[98:99]
	ds_add_f32 v34, v240
	ds_add_f32 v34, v241 offset:4
	ds_add_f32 v34, v242 offset:8
	ds_add_f32 v34, v243 offset:12
	s_or_b64 exec, exec, s[100:101]
	s_waitcnt lgkmcnt(0)
	ds_read_b128 v[34:37], v214
	ds_read_b128 v[38:41], v214 offset:32
	s_mov_b64 s[4:5], -1
	s_and_b64 vcc, exec, s[42:43]
	s_waitcnt lgkmcnt(1)
	v_rcp_f32_e32 v89, v34
	v_rcp_f32_e32 v90, v35
	v_rcp_f32_e32 v91, v36
	v_rcp_f32_e32 v92, v37
	s_waitcnt lgkmcnt(0)
	v_rcp_f32_e32 v93, v38
	ds_read_b128 v[34:37], v214 offset:64
	v_rcp_f32_e32 v94, v39
	v_rcp_f32_e32 v95, v40
	v_rcp_f32_e32 v96, v41
	ds_read_b128 v[38:41], v214 offset:96
	s_waitcnt lgkmcnt(1)
	v_rcp_f32_e32 v97, v34
	v_rcp_f32_e32 v98, v35
	v_rcp_f32_e32 v99, v36
	v_rcp_f32_e32 v100, v37
	s_waitcnt lgkmcnt(0)
	v_rcp_f32_e32 v101, v38
	v_rcp_f32_e32 v102, v39
	v_rcp_f32_e32 v103, v40
	v_rcp_f32_e32 v34, v41
	v_mul_f32_e32 v87, v50, v89
	v_mul_f32_e32 v86, v51, v90
	v_mul_f32_e32 v85, v52, v91
	v_mul_f32_e32 v84, v53, v92
	v_mul_f32_e32 v83, v54, v93
	v_mul_f32_e32 v82, v55, v94
	v_mul_f32_e32 v53, v56, v95
	v_mul_f32_e32 v50, v57, v96
	v_mul_f32_e32 v48, v58, v97
	v_mul_f32_e32 v46, v59, v98
	v_mul_f32_e32 v44, v60, v99
	v_mul_f32_e32 v42, v61, v100
	v_mul_f32_e32 v40, v62, v101
	v_mul_f32_e32 v38, v63, v102
	v_mul_f32_e32 v36, v64, v103
	v_mul_f32_e32 v35, v65, v34
	v_mul_f32_e32 v88, v66, v89
	v_mul_f32_e32 v66, v67, v90
	v_mul_f32_e32 v64, v68, v91
	v_mul_f32_e32 v62, v69, v92
	v_mul_f32_e32 v60, v70, v93
	v_mul_f32_e32 v58, v71, v94
	v_mul_f32_e32 v56, v72, v95
	v_mul_f32_e32 v54, v73, v96
	v_mul_f32_e32 v51, v74, v97
	v_mul_f32_e32 v49, v75, v98
	v_mul_f32_e32 v47, v76, v99
	v_mul_f32_e32 v45, v77, v100
	v_mul_f32_e32 v43, v78, v101
	v_mul_f32_e32 v41, v79, v102
	v_mul_f32_e32 v39, v80, v103
	v_mul_f32_e32 v37, v81, v34
	v_mul_f32_e32 v70, v2, v89
	v_mul_f32_e32 v68, v3, v90
	v_mul_f32_e32 v67, v4, v91
	v_mul_f32_e32 v65, v5, v92
	v_mul_f32_e32 v63, v6, v93
	v_mul_f32_e32 v61, v7, v94
	v_mul_f32_e32 v59, v8, v95
	v_mul_f32_e32 v57, v9, v96
	v_mul_f32_e32 v55, v10, v97
	v_mul_f32_e32 v52, v11, v98
	v_mul_f32_e32 v11, v12, v99
	v_mul_f32_e32 v9, v13, v100
	v_mul_f32_e32 v7, v14, v101
	v_mul_f32_e32 v5, v15, v102
	v_mul_f32_e32 v4, v16, v103
	v_mul_f32_e32 v72, v18, v89
	v_mul_f32_e32 v71, v19, v90
	v_mul_f32_e32 v69, v20, v91
	v_mul_f32_e32 v21, v21, v92
	v_mul_f32_e32 v20, v22, v93
	v_mul_f32_e32 v19, v23, v94
	v_mul_f32_e32 v18, v24, v95
	v_mul_f32_e32 v16, v25, v96
	v_mul_f32_e32 v15, v26, v97
	v_mul_f32_e32 v14, v27, v98
	v_mul_f32_e32 v13, v28, v99
	v_mul_f32_e32 v12, v29, v100
	v_mul_f32_e32 v10, v30, v101
	v_mul_f32_e32 v8, v31, v102
	v_mul_f32_e32 v6, v32, v103
	s_cbranch_vccz .LBB0_533
; __device__ __forceinline__ int crow(int r, int hi) { return (r & 3) + 8 * (r >> 2) + 4 * hi; }
; __device__ __forceinline__ int crow(int r, int hi) { return (r & 3) + 8 * (r >> 2) + 4 * hi; }
; template <int NCB, bool DIFF, bool STAT>
; __device__ __forceinline__ void attn_unit(LAS char* lds, const Params& P, int s, int head, int qb, float sref) {
;     ...
;                 const float lam = *(const float*)(ws + WS_LAM);
;                 float ss[16];
; #pragma unroll
;                 for (int r = 0; r < 16; ++r) ss[r] = 0.f;
; #pragma unroll
;                 for (int d0 = 0; d0 < NCB; ++d0)
; #pragma unroll
;                     for (int r = 0; r < 16; ++r) { const float o1 = bf2f(mixw[(size_t)crow(r, hi) * DM + 512 + head * 128 + d0 * 32 + r32]);
;                         const float a0 = o1 - lam * (o[d0][r] * rli[r]); o[d0][r] = a0; ss[r] += a0 * a0; }
	global_load_dword v2, v0, s[10:11]
	global_load_ushort v150, v[172:173], off offset:1024
	global_load_ushort v151, v[172:173], off offset:3072
	global_load_ushort v152, v[174:175], off
	global_load_ushort v153, v[176:177], off
	global_load_ushort v154, v[178:179], off
	global_load_ushort v155, v[180:181], off
	global_load_ushort v156, v[182:183], off
	global_load_ushort v157, v[184:185], off
	global_load_ushort v158, v[186:187], off
	global_load_ushort v159, v[188:189], off
	global_load_ushort v160, v[190:191], off
	global_load_ushort v161, v[192:193], off
	global_load_ushort v162, v[194:195], off
	global_load_ushort v163, v[196:197], off
	global_load_ushort v164, v[198:199], off
	global_load_ushort v165, v[200:201], off
	global_load_ushort v166, v[172:173], off offset:1088
	global_load_ushort v167, v[172:173], off offset:3136
	global_load_ushort v168, v[174:175], off offset:64
	global_load_ushort v169, v[176:177], off offset:64
	global_load_ushort v216, v[178:179], off offset:64
	global_load_ushort v218, v[180:181], off offset:64
	global_load_ushort v219, v[182:183], off offset:64
	global_load_ushort v220, v[184:185], off offset:64
	global_load_ushort v221, v[186:187], off offset:64
	global_load_ushort v222, v[188:189], off offset:64
	global_load_ushort v223, v[190:191], off offset:64
	global_load_ushort v224, v[192:193], off offset:64
	global_load_ushort v225, v[194:195], off offset:64
	global_load_ushort v226, v[196:197], off offset:64
	global_load_ushort v227, v[198:199], off offset:64
	global_load_ushort v228, v[200:201], off offset:64
	global_load_ushort v229, v[172:173], off offset:1152
	global_load_ushort v236, v[172:173], off offset:3200
	global_load_ushort v237, v[174:175], off offset:128
	global_load_ushort v238, v[176:177], off offset:128
	global_load_ushort v239, v[178:179], off offset:128
	global_load_ushort v240, v[180:181], off offset:128
	global_load_ushort v241, v[182:183], off offset:128
	global_load_ushort v242, v[184:185], off offset:128
	global_load_ushort v243, v[186:187], off offset:128
	global_load_ushort v244, v[188:189], off offset:128
	global_load_ushort v245, v[190:191], off offset:128
	global_load_ushort v246, v[192:193], off offset:128
	global_load_ushort v247, v[194:195], off offset:128
	global_load_ushort v248, v[196:197], off offset:128
	global_load_ushort v249, v[198:199], off offset:128
	global_load_ushort v250, v[200:201], off offset:128
	global_load_ushort v251, v[172:173], off offset:1216
	global_load_ushort v252, v[172:173], off offset:3264
	global_load_ushort v253, v[174:175], off offset:192
	s_mov_b64 s[4:5], 0
	s_waitcnt vmcnt(50)
	v_lshlrev_b32_e32 v150, 16, v150
	v_fma_f32 v78, -v87, v2, v150
	s_waitcnt vmcnt(49)
	v_lshlrev_b32_e32 v151, 16, v151
	v_fma_f32 v77, -v86, v2, v151
	s_waitcnt vmcnt(48)
	v_lshlrev_b32_e32 v152, 16, v152
	v_fma_f32 v76, -v85, v2, v152
	s_waitcnt vmcnt(47)
	v_lshlrev_b32_e32 v153, 16, v153
	v_fma_f32 v75, -v84, v2, v153
	s_waitcnt vmcnt(46)
	v_lshlrev_b32_e32 v154, 16, v154
	v_fma_f32 v74, -v83, v2, v154
	s_waitcnt vmcnt(45)
	v_lshlrev_b32_e32 v155, 16, v155
	v_fma_f32 v73, -v82, v2, v155
	s_waitcnt vmcnt(44)
	v_lshlrev_b32_e32 v156, 16, v156
	v_fma_f32 v31, -v53, v2, v156
	s_waitcnt vmcnt(43)
	v_lshlrev_b32_e32 v157, 16, v157
	v_fma_f32 v30, -v50, v2, v157
	s_waitcnt vmcnt(42)
	v_lshlrev_b32_e32 v158, 16, v158
	v_fma_f32 v29, -v48, v2, v158
	s_waitcnt vmcnt(41)
	v_lshlrev_b32_e32 v159, 16, v159
	v_fma_f32 v28, -v46, v2, v159
	s_waitcnt vmcnt(40)
	v_lshlrev_b32_e32 v160, 16, v160
	v_fma_f32 v27, -v44, v2, v160
	s_waitcnt vmcnt(39)
	v_lshlrev_b32_e32 v161, 16, v161
	v_fma_f32 v26, -v42, v2, v161
	s_waitcnt vmcnt(38)
	v_lshlrev_b32_e32 v162, 16, v162
	v_fma_f32 v25, -v40, v2, v162
	global_load_ushort v150, v[176:177], off offset:192
	global_load_ushort v151, v[178:179], off offset:192
	global_load_ushort v152, v[180:181], off offset:192
	global_load_ushort v153, v[182:183], off offset:192
	global_load_ushort v154, v[184:185], off offset:192
	global_load_ushort v155, v[186:187], off offset:192
	global_load_ushort v156, v[188:189], off offset:192
	global_load_ushort v157, v[190:191], off offset:192
	global_load_ushort v158, v[192:193], off offset:192
	global_load_ushort v159, v[194:195], off offset:192
	global_load_ushort v160, v[196:197], off offset:192
	global_load_ushort v161, v[198:199], off offset:192
	global_load_ushort v162, v[200:201], off offset:192
	s_waitcnt vmcnt(50)
	v_lshlrev_b32_e32 v163, 16, v163
	v_fma_f32 v24, -v38, v2, v163
	s_waitcnt vmcnt(49)
	v_lshlrev_b32_e32 v164, 16, v164
	v_fma_f32 v23, -v36, v2, v164
	s_waitcnt vmcnt(48)
	v_lshlrev_b32_e32 v165, 16, v165
	v_fma_f32 v22, -v35, v2, v165
	s_waitcnt vmcnt(47)
	v_lshlrev_b32_e32 v166, 16, v166
	v_fma_f32 v95, -v88, v2, v166
	v_mul_f32_e32 v146, v95, v95
	v_fmac_f32_e32 v146, v78, v78
	s_waitcnt vmcnt(46)
	v_lshlrev_b32_e32 v167, 16, v167
	v_fma_f32 v96, -v66, v2, v167
	v_mul_f32_e32 v145, v96, v96
	v_fmac_f32_e32 v145, v77, v77
	s_waitcnt vmcnt(45)
	v_lshlrev_b32_e32 v168, 16, v168
	v_fma_f32 v97, -v64, v2, v168
	v_mul_f32_e32 v144, v97, v97
	v_fmac_f32_e32 v144, v76, v76
	s_waitcnt vmcnt(44)
	v_lshlrev_b32_e32 v169, 16, v169
	v_fma_f32 v94, -v62, v2, v169
	v_mul_f32_e32 v143, v94, v94
	v_fmac_f32_e32 v143, v75, v75
	s_waitcnt vmcnt(43)
	v_lshlrev_b32_e32 v216, 16, v216
	v_fma_f32 v93, -v60, v2, v216
	v_mul_f32_e32 v142, v93, v93
	v_fmac_f32_e32 v142, v74, v74
	s_waitcnt vmcnt(42)
	v_lshlrev_b32_e32 v218, 16, v218
	v_fma_f32 v92, -v58, v2, v218
	v_mul_f32_e32 v141, v92, v92
	v_fmac_f32_e32 v141, v73, v73
	s_waitcnt vmcnt(41)
; __device__ __forceinline__ int crow(int r, int hi) { return (r & 3) + 8 * (r >> 2) + 4 * hi; }
; __device__ __forceinline__ int crow(int r, int hi) { return (r & 3) + 8 * (r >> 2) + 4 * hi; }
; template <int NCB, bool DIFF, bool STAT>
; __device__ __forceinline__ void attn_unit(LAS char* lds, const Params& P, int s, int head, int qb, float sref) {
;     ...
;                 for (int d0 = 0; d0 < NCB; ++d0)
; #pragma unroll
;                     for (int r = 0; r < 16; ++r) { const float o1 = bf2f(mixw[(size_t)crow(r, hi) * DM + 512 + head * 128 + d0 * 32 + r32]);
;                         const float a0 = o1 - lam * (o[d0][r] * rli[r]); o[d0][r] = a0; ss[r] += a0 * a0; }
	v_lshlrev_b32_e32 v219, 16, v219
	v_fma_f32 v91, -v56, v2, v219
	v_mul_f32_e32 v140, v91, v91
	v_fmac_f32_e32 v140, v31, v31
	s_waitcnt vmcnt(40)
	v_lshlrev_b32_e32 v220, 16, v220
	v_fma_f32 v90, -v54, v2, v220
	v_mul_f32_e32 v139, v90, v90
	v_fmac_f32_e32 v139, v30, v30
	s_waitcnt vmcnt(39)
	v_lshlrev_b32_e32 v221, 16, v221
	v_fma_f32 v89, -v51, v2, v221
	v_mul_f32_e32 v138, v89, v89
	v_fmac_f32_e32 v138, v29, v29
	s_waitcnt vmcnt(38)
	v_lshlrev_b32_e32 v222, 16, v222
	v_fma_f32 v81, -v49, v2, v222
	v_mul_f32_e32 v132, v81, v81
	v_fmac_f32_e32 v132, v28, v28
	s_waitcnt vmcnt(37)
	v_lshlrev_b32_e32 v223, 16, v223
	v_fma_f32 v80, -v47, v2, v223
	v_mul_f32_e32 v126, v80, v80
	v_fmac_f32_e32 v126, v27, v27
	s_waitcnt vmcnt(36)
	v_lshlrev_b32_e32 v224, 16, v224
	v_fma_f32 v79, -v45, v2, v224
	v_mul_f32_e32 v118, v79, v79
	v_fmac_f32_e32 v118, v26, v26
	s_waitcnt vmcnt(35)
	v_lshlrev_b32_e32 v225, 16, v225
	v_fma_f32 v98, -v43, v2, v225
	v_mul_f32_e32 v134, v98, v98
	v_fmac_f32_e32 v134, v25, v25
	s_waitcnt vmcnt(34)
	v_lshlrev_b32_e32 v226, 16, v226
	v_fma_f32 v99, -v41, v2, v226
	v_mul_f32_e32 v136, v99, v99
	v_fmac_f32_e32 v136, v24, v24
	s_waitcnt vmcnt(33)
	v_lshlrev_b32_e32 v227, 16, v227
	v_fma_f32 v100, -v39, v2, v227
	v_mul_f32_e32 v137, v100, v100
	v_fmac_f32_e32 v137, v23, v23
	s_waitcnt vmcnt(32)
	v_lshlrev_b32_e32 v228, 16, v228
	v_fma_f32 v101, -v37, v2, v228
	v_mul_f32_e32 v147, v101, v101
	v_fmac_f32_e32 v147, v22, v22
	s_waitcnt vmcnt(31)
	v_lshlrev_b32_e32 v229, 16, v229
	v_fma_f32 v116, -v70, v2, v229
	v_fmac_f32_e32 v146, v116, v116
	s_waitcnt vmcnt(30)
	v_lshlrev_b32_e32 v236, 16, v236
	v_fma_f32 v115, -v68, v2, v236
	v_fmac_f32_e32 v145, v115, v115
	s_waitcnt vmcnt(29)
	v_lshlrev_b32_e32 v237, 16, v237
	v_fma_f32 v114, -v67, v2, v237
	v_fmac_f32_e32 v144, v114, v114
	s_waitcnt vmcnt(28)
	v_lshlrev_b32_e32 v238, 16, v238
	v_fma_f32 v113, -v65, v2, v238
	v_fmac_f32_e32 v143, v113, v113
	s_waitcnt vmcnt(27)
	v_lshlrev_b32_e32 v239, 16, v239
	v_fma_f32 v112, -v63, v2, v239
	v_fmac_f32_e32 v142, v112, v112
	s_waitcnt vmcnt(26)
	v_lshlrev_b32_e32 v240, 16, v240
	v_fma_f32 v111, -v61, v2, v240
	v_fmac_f32_e32 v141, v111, v111
	s_waitcnt vmcnt(25)
	v_lshlrev_b32_e32 v241, 16, v241
	v_fma_f32 v110, -v59, v2, v241
	v_fmac_f32_e32 v140, v110, v110
	s_waitcnt vmcnt(24)
	v_lshlrev_b32_e32 v242, 16, v242
	v_fma_f32 v109, -v57, v2, v242
	v_fmac_f32_e32 v139, v109, v109
	s_waitcnt vmcnt(23)
	v_lshlrev_b32_e32 v243, 16, v243
	v_fma_f32 v108, -v55, v2, v243
	v_fmac_f32_e32 v138, v108, v108
	s_waitcnt vmcnt(22)
	v_lshlrev_b32_e32 v244, 16, v244
	v_fma_f32 v107, -v52, v2, v244
	v_fmac_f32_e32 v132, v107, v107
	s_waitcnt vmcnt(21)
	v_lshlrev_b32_e32 v245, 16, v245
	v_fma_f32 v106, -v11, v2, v245
	v_fmac_f32_e32 v126, v106, v106
	s_waitcnt vmcnt(20)
	v_lshlrev_b32_e32 v246, 16, v246
	v_fma_f32 v105, -v9, v2, v246
	v_fmac_f32_e32 v118, v105, v105
	s_waitcnt vmcnt(19)
	v_lshlrev_b32_e32 v247, 16, v247
	v_fma_f32 v104, -v7, v2, v247
	v_fmac_f32_e32 v134, v104, v104
	s_waitcnt vmcnt(18)
	v_lshlrev_b32_e32 v248, 16, v248
	v_fma_f32 v103, -v5, v2, v248
	v_fmac_f32_e32 v136, v103, v103
	s_waitcnt vmcnt(17)
	v_lshlrev_b32_e32 v249, 16, v249
	v_fma_f32 v102, -v4, v2, v249
	v_fmac_f32_e32 v137, v102, v102
	s_waitcnt vmcnt(16)
	v_lshlrev_b32_e32 v148, 16, v250
	s_waitcnt vmcnt(15)
	v_lshlrev_b32_e32 v251, 16, v251
	v_fma_f32 v117, -v72, v2, v251
	v_fmac_f32_e32 v146, v117, v117
	s_waitcnt vmcnt(14)
	v_lshlrev_b32_e32 v252, 16, v252
	v_fma_f32 v121, -v71, v2, v252
	v_fmac_f32_e32 v145, v121, v121
	s_waitcnt vmcnt(13)
	v_lshlrev_b32_e32 v253, 16, v253
	v_fma_f32 v119, -v69, v2, v253
	v_fmac_f32_e32 v144, v119, v119
	s_waitcnt vmcnt(12)
	v_lshlrev_b32_e32 v150, 16, v150
	v_fma_f32 v122, -v21, v2, v150
	v_fmac_f32_e32 v143, v122, v122
	s_waitcnt vmcnt(11)
	v_lshlrev_b32_e32 v151, 16, v151
	v_fma_f32 v120, -v20, v2, v151
	v_fmac_f32_e32 v142, v120, v120
	s_waitcnt vmcnt(10)
	v_lshlrev_b32_e32 v152, 16, v152
	v_fma_f32 v124, -v19, v2, v152
	v_fmac_f32_e32 v141, v124, v124
	s_waitcnt vmcnt(9)
	v_lshlrev_b32_e32 v153, 16, v153
	v_fma_f32 v123, -v18, v2, v153
	v_fmac_f32_e32 v140, v123, v123
	s_waitcnt vmcnt(8)
	v_lshlrev_b32_e32 v154, 16, v154
	v_fma_f32 v127, -v16, v2, v154
	v_fmac_f32_e32 v139, v127, v127
	s_waitcnt vmcnt(7)
	v_lshlrev_b32_e32 v155, 16, v155
	v_fma_f32 v125, -v15, v2, v155
	v_fmac_f32_e32 v138, v125, v125
	s_waitcnt vmcnt(6)
	v_lshlrev_b32_e32 v156, 16, v156
	v_fma_f32 v129, -v14, v2, v156
	v_fmac_f32_e32 v132, v129, v129
	s_waitcnt vmcnt(5)
	v_lshlrev_b32_e32 v157, 16, v157
	v_fma_f32 v128, -v13, v2, v157
	v_fmac_f32_e32 v126, v128, v128
	s_waitcnt vmcnt(4)
	v_lshlrev_b32_e32 v158, 16, v158
	v_fma_f32 v131, -v12, v2, v158
	v_fmac_f32_e32 v118, v131, v131
	s_waitcnt vmcnt(3)
	v_lshlrev_b32_e32 v159, 16, v159
	v_fma_f32 v130, -v10, v2, v159
	v_fmac_f32_e32 v134, v130, v130
	s_waitcnt vmcnt(2)
	v_lshlrev_b32_e32 v160, 16, v160
	v_fma_f32 v135, -v8, v2, v160
	v_fmac_f32_e32 v136, v135, v135
	s_waitcnt vmcnt(1)
	v_lshlrev_b32_e32 v161, 16, v161
	v_fma_f32 v133, -v6, v2, v161
	v_fmac_f32_e32 v137, v133, v133
	s_waitcnt vmcnt(0)
; template <int NCB, bool DIFF, bool STAT>
; __device__ __forceinline__ void attn_unit(LAS char* lds, const Params& P, int s, int head, int qb, float sref) {
;     ...
;                         const float a0 = o1 - lam * (o[d0][r] * rli[r]); o[d0][r] = a0; ss[r] += a0 * a0; }
; #pragma unroll
;                 for (int r = 0; r < 16; ++r) {
; #pragma unroll
;                     for (int of = 1; of < 32; of <<= 1) ss[r] += __shfl_xor(ss[r], of);
;                     ss[r] = __builtin_amdgcn_rsqf(ss[r] * (1.0f / 128.0f) + EPS) * 0.8f;
	v_lshlrev_b32_e32 v149, 16, v162
	v_mov_b32_e32 v32, v17
	v_pk_mul_f32 v[150:151], v[32:33], v[34:35] op_sel_hi:[1,0]
	s_nop 0
	v_pk_fma_f32 v[2:3], v[150:151], v[2:3], v[148:149] op_sel_hi:[1,0,1] neg_lo:[1,0,0] neg_hi:[1,0,0]
	s_nop 0
	v_pk_mul_f32 v[148:149], v[2:3], v[2:3]
	s_nop 0
	v_add_f32_e32 v32, v147, v148
	v_add_f32_e32 v32, v32, v149
	v_and_b32_e32 v147, 64, v235
	v_add_u32_e32 v151, 64, v147
	v_xor_b32_e32 v147, 1, v235
	v_cmp_lt_i32_e32 vcc, v147, v151
	s_nop 1
	v_cndmask_b32_e32 v147, v235, v147, vcc
	v_lshlrev_b32_e32 v147, 2, v147
	v_xor_b32_e32 v148, 2, v235
	v_cmp_lt_i32_e32 vcc, v148, v151
	s_nop 1
	v_cndmask_b32_e32 v148, v235, v148, vcc
	v_lshlrev_b32_e32 v148, 2, v148
	v_xor_b32_e32 v149, 4, v235
	v_cmp_lt_i32_e32 vcc, v149, v151
	s_nop 1
	v_cndmask_b32_e32 v149, v235, v149, vcc
	v_lshlrev_b32_e32 v149, 2, v149
	v_xor_b32_e32 v150, 8, v235
	v_cmp_lt_i32_e32 vcc, v150, v151
	s_nop 1
	v_cndmask_b32_e32 v150, v235, v150, vcc
	v_lshlrev_b32_e32 v150, 2, v150
	v_xor_b32_e32 v154, 16, v235
	v_cmp_lt_i32_e32 vcc, v154, v151
	s_nop 1
	v_cndmask_b32_e32 v151, v235, v154, vcc
	v_lshlrev_b32_e32 v151, 2, v151
	ds_bpermute_b32 v154, v147, v146
	ds_bpermute_b32 v155, v147, v145
	ds_bpermute_b32 v156, v147, v144
	ds_bpermute_b32 v157, v147, v143
	ds_bpermute_b32 v158, v147, v142
	ds_bpermute_b32 v159, v147, v141
	ds_bpermute_b32 v160, v147, v140
	ds_bpermute_b32 v161, v147, v139
	s_waitcnt lgkmcnt(7)
	v_add_f32_e32 v146, v146, v154
	ds_bpermute_b32 v162, v147, v138
	s_waitcnt lgkmcnt(7)
	v_add_f32_e32 v145, v145, v155
	ds_bpermute_b32 v163, v147, v132
	s_waitcnt lgkmcnt(7)
	v_add_f32_e32 v144, v144, v156
	ds_bpermute_b32 v164, v147, v126
	s_waitcnt lgkmcnt(7)
	v_add_f32_e32 v143, v143, v157
	ds_bpermute_b32 v165, v147, v118
	s_waitcnt lgkmcnt(7)
	v_add_f32_e32 v142, v142, v158
	ds_bpermute_b32 v166, v147, v134
	s_waitcnt lgkmcnt(7)
	v_add_f32_e32 v141, v141, v159
	ds_bpermute_b32 v167, v147, v136
	s_waitcnt lgkmcnt(7)
	v_add_f32_e32 v140, v140, v160
	ds_bpermute_b32 v168, v147, v137
	s_waitcnt lgkmcnt(7)
	v_add_f32_e32 v139, v139, v161
	ds_bpermute_b32 v169, v147, v32
	s_waitcnt lgkmcnt(7)
	v_add_f32_e32 v138, v138, v162
	s_waitcnt lgkmcnt(6)
	v_add_f32_e32 v132, v132, v163
	s_waitcnt lgkmcnt(5)
	v_add_f32_e32 v126, v126, v164
	s_waitcnt lgkmcnt(4)
	v_add_f32_e32 v118, v118, v165
	s_waitcnt lgkmcnt(3)
	v_add_f32_e32 v134, v134, v166
	s_waitcnt lgkmcnt(2)
	v_add_f32_e32 v136, v136, v167
	s_waitcnt lgkmcnt(1)
	v_add_f32_e32 v137, v137, v168
	s_waitcnt lgkmcnt(0)
	v_add_f32_e32 v32, v32, v169
	ds_bpermute_b32 v154, v148, v146
	ds_bpermute_b32 v155, v148, v145
	ds_bpermute_b32 v156, v148, v144
	ds_bpermute_b32 v157, v148, v143
	ds_bpermute_b32 v158, v148, v142
	ds_bpermute_b32 v159, v148, v141
	ds_bpermute_b32 v160, v148, v140
	ds_bpermute_b32 v161, v148, v139
	s_waitcnt lgkmcnt(7)
	v_add_f32_e32 v146, v146, v154
	ds_bpermute_b32 v162, v148, v138
	s_waitcnt lgkmcnt(7)
	v_add_f32_e32 v145, v145, v155
	ds_bpermute_b32 v163, v148, v132
	s_waitcnt lgkmcnt(7)
	v_add_f32_e32 v144, v144, v156
	ds_bpermute_b32 v164, v148, v126
	s_waitcnt lgkmcnt(7)
	v_add_f32_e32 v143, v143, v157
	ds_bpermute_b32 v165, v148, v118
	s_waitcnt lgkmcnt(7)
	v_add_f32_e32 v142, v142, v158
	ds_bpermute_b32 v166, v148, v134
	s_waitcnt lgkmcnt(7)
	v_add_f32_e32 v141, v141, v159
	ds_bpermute_b32 v167, v148, v136
	s_waitcnt lgkmcnt(7)
	v_add_f32_e32 v140, v140, v160
	ds_bpermute_b32 v168, v148, v137
	s_waitcnt lgkmcnt(7)
	v_add_f32_e32 v139, v139, v161
	ds_bpermute_b32 v169, v148, v32
	s_waitcnt lgkmcnt(7)
	v_add_f32_e32 v138, v138, v162
	s_waitcnt lgkmcnt(6)
	v_add_f32_e32 v132, v132, v163
	s_waitcnt lgkmcnt(5)
	v_add_f32_e32 v126, v126, v164
	s_waitcnt lgkmcnt(4)
	v_add_f32_e32 v118, v118, v165
	s_waitcnt lgkmcnt(3)
	v_add_f32_e32 v134, v134, v166
	s_waitcnt lgkmcnt(2)
	v_add_f32_e32 v136, v136, v167
	s_waitcnt lgkmcnt(1)
	v_add_f32_e32 v137, v137, v168
	s_waitcnt lgkmcnt(0)
	v_add_f32_e32 v32, v32, v169
	ds_bpermute_b32 v154, v149, v146
	ds_bpermute_b32 v155, v149, v145
	ds_bpermute_b32 v156, v149, v144
	ds_bpermute_b32 v157, v149, v143
	ds_bpermute_b32 v158, v149, v142
	ds_bpermute_b32 v159, v149, v141
	ds_bpermute_b32 v160, v149, v140
	ds_bpermute_b32 v161, v149, v139
	s_waitcnt lgkmcnt(7)
	v_add_f32_e32 v146, v146, v154
	ds_bpermute_b32 v162, v149, v138
	s_waitcnt lgkmcnt(7)
	v_add_f32_e32 v145, v145, v155
	ds_bpermute_b32 v163, v149, v132
	s_waitcnt lgkmcnt(7)
	v_add_f32_e32 v144, v144, v156
	ds_bpermute_b32 v164, v149, v126
	s_waitcnt lgkmcnt(7)
	v_add_f32_e32 v143, v143, v157
	ds_bpermute_b32 v165, v149, v118
	s_waitcnt lgkmcnt(7)
	v_add_f32_e32 v142, v142, v158
	ds_bpermute_b32 v166, v149, v134
	s_waitcnt lgkmcnt(7)
	v_add_f32_e32 v141, v141, v159
	ds_bpermute_b32 v167, v149, v136
	s_waitcnt lgkmcnt(7)
	v_add_f32_e32 v140, v140, v160
	ds_bpermute_b32 v168, v149, v137
	s_waitcnt lgkmcnt(7)
	v_add_f32_e32 v139, v139, v161
	ds_bpermute_b32 v169, v149, v32
	s_waitcnt lgkmcnt(7)
	v_add_f32_e32 v138, v138, v162
	s_waitcnt lgkmcnt(6)
	v_add_f32_e32 v132, v132, v163
	s_waitcnt lgkmcnt(5)
	v_add_f32_e32 v126, v126, v164
	s_waitcnt lgkmcnt(4)
	v_add_f32_e32 v118, v118, v165
	s_waitcnt lgkmcnt(3)
	v_add_f32_e32 v134, v134, v166
	s_waitcnt lgkmcnt(2)
	v_add_f32_e32 v136, v136, v167
	s_waitcnt lgkmcnt(1)
	v_add_f32_e32 v137, v137, v168
	s_waitcnt lgkmcnt(0)
	v_add_f32_e32 v32, v32, v169
	ds_bpermute_b32 v154, v150, v146
	ds_bpermute_b32 v155, v150, v145
	ds_bpermute_b32 v156, v150, v144
	ds_bpermute_b32 v157, v150, v143
	ds_bpermute_b32 v158, v150, v142
	ds_bpermute_b32 v159, v150, v141
	ds_bpermute_b32 v160, v150, v140
	ds_bpermute_b32 v161, v150, v139
	s_waitcnt lgkmcnt(7)
; __device__ __forceinline__ unsigned f2bf(float f) { unsigned u = __builtin_bit_cast(unsigned, f); return (u + 0x7fffu + ((u >> 16) & 1u)) >> 16; }
; __device__ __forceinline__ int crow(int r, int hi) { return (r & 3) + 8 * (r >> 2) + 4 * hi; }
; __device__ __forceinline__ int crow(int r, int hi) { return (r & 3) + 8 * (r >> 2) + 4 * hi; }
; template <int NCB, bool DIFF, bool STAT>
; __device__ __forceinline__ void attn_unit(LAS char* lds, const Params& P, int s, int head, int qb, float sref) {
;     ...
; #pragma unroll
;                 for (int r = 0; r < 16; ++r) {
; #pragma unroll
;                     for (int of = 1; of < 32; of <<= 1) ss[r] += __shfl_xor(ss[r], of);
;                     ss[r] = __builtin_amdgcn_rsqf(ss[r] * (1.0f / 128.0f) + EPS) * 0.8f;
;                 }
;                 float gs[NCB];
; #pragma unroll
;                 for (int d0 = 0; d0 < NCB; ++d0) gs[d0] = P.in[15][d0 * 32 + r32];
; #pragma unroll
;                 for (int r = 0; r < 16; ++r) { const int orow = crow(r, hi);
; #pragma unroll
;                     for (int d0 = 0; d0 < NCB; ++d0) mixw[(size_t)orow * DM + 512 + head * 128 + d0 * 32 + r32] = (bf16)f2bf(o[d0][r] * ss[r] * gs[d0]); }
	v_add_f32_e32 v146, v146, v154
	ds_bpermute_b32 v162, v150, v138
	s_waitcnt lgkmcnt(7)
	v_add_f32_e32 v145, v145, v155
	ds_bpermute_b32 v163, v150, v132
	s_waitcnt lgkmcnt(7)
	v_add_f32_e32 v144, v144, v156
	ds_bpermute_b32 v164, v150, v126
	s_waitcnt lgkmcnt(7)
	v_add_f32_e32 v143, v143, v157
	ds_bpermute_b32 v165, v150, v118
	s_waitcnt lgkmcnt(7)
	v_add_f32_e32 v142, v142, v158
	ds_bpermute_b32 v166, v150, v134
	s_waitcnt lgkmcnt(7)
	v_add_f32_e32 v141, v141, v159
	ds_bpermute_b32 v167, v150, v136
	s_waitcnt lgkmcnt(7)
	v_add_f32_e32 v140, v140, v160
	ds_bpermute_b32 v168, v150, v137
	s_waitcnt lgkmcnt(7)
	v_add_f32_e32 v139, v139, v161
	ds_bpermute_b32 v169, v150, v32
	s_waitcnt lgkmcnt(7)
	v_add_f32_e32 v138, v138, v162
	s_waitcnt lgkmcnt(6)
	v_add_f32_e32 v132, v132, v163
	s_waitcnt lgkmcnt(5)
	v_add_f32_e32 v126, v126, v164
	s_waitcnt lgkmcnt(4)
	v_add_f32_e32 v118, v118, v165
	s_waitcnt lgkmcnt(3)
	v_add_f32_e32 v134, v134, v166
	s_waitcnt lgkmcnt(2)
	v_add_f32_e32 v136, v136, v167
	s_waitcnt lgkmcnt(1)
	v_add_f32_e32 v137, v137, v168
	s_waitcnt lgkmcnt(0)
	v_add_f32_e32 v32, v32, v169
	ds_bpermute_b32 v154, v151, v146
	ds_bpermute_b32 v155, v151, v145
	ds_bpermute_b32 v156, v151, v144
	ds_bpermute_b32 v157, v151, v143
	ds_bpermute_b32 v158, v151, v142
	ds_bpermute_b32 v159, v151, v141
	ds_bpermute_b32 v160, v151, v140
	ds_bpermute_b32 v161, v151, v139
	s_waitcnt lgkmcnt(7)
	v_add_f32_e32 v146, v146, v154
	ds_bpermute_b32 v162, v151, v138
	s_waitcnt lgkmcnt(7)
	v_add_f32_e32 v145, v145, v155
	ds_bpermute_b32 v163, v151, v132
	s_waitcnt lgkmcnt(7)
	v_add_f32_e32 v144, v144, v156
	ds_bpermute_b32 v164, v151, v126
	s_waitcnt lgkmcnt(7)
	v_add_f32_e32 v143, v143, v157
	ds_bpermute_b32 v165, v151, v118
	s_waitcnt lgkmcnt(7)
	v_add_f32_e32 v142, v142, v158
	ds_bpermute_b32 v166, v151, v134
	s_waitcnt lgkmcnt(7)
	v_add_f32_e32 v141, v141, v159
	ds_bpermute_b32 v167, v151, v136
	s_waitcnt lgkmcnt(7)
	v_add_f32_e32 v140, v140, v160
	ds_bpermute_b32 v168, v151, v137
	s_waitcnt lgkmcnt(7)
	v_add_f32_e32 v139, v139, v161
	ds_bpermute_b32 v169, v151, v32
	s_waitcnt lgkmcnt(7)
	v_add_f32_e32 v138, v138, v162
	s_waitcnt lgkmcnt(6)
	v_add_f32_e32 v132, v132, v163
	s_waitcnt lgkmcnt(5)
	v_add_f32_e32 v126, v126, v164
	s_waitcnt lgkmcnt(4)
	v_add_f32_e32 v118, v118, v165
	s_waitcnt lgkmcnt(3)
	v_add_f32_e32 v134, v134, v166
	s_waitcnt lgkmcnt(2)
	v_add_f32_e32 v136, v136, v167
	s_waitcnt lgkmcnt(1)
	v_add_f32_e32 v137, v137, v168
	s_waitcnt lgkmcnt(0)
	v_add_f32_e32 v32, v32, v169
	v_fmamk_f32 v146, v146, 0x3c000000, v234
	v_fmamk_f32 v145, v145, 0x3c000000, v234
	v_fmamk_f32 v144, v144, 0x3c000000, v234
	v_fmamk_f32 v143, v143, 0x3c000000, v234
	v_fmamk_f32 v142, v142, 0x3c000000, v234
	v_fmamk_f32 v141, v141, 0x3c000000, v234
	v_fmamk_f32 v140, v140, 0x3c000000, v234
	v_fmamk_f32 v139, v139, 0x3c000000, v234
	v_fmamk_f32 v138, v138, 0x3c000000, v234
	v_fmamk_f32 v132, v132, 0x3c000000, v234
	v_fmamk_f32 v126, v126, 0x3c000000, v234
	v_fmamk_f32 v118, v118, 0x3c000000, v234
	v_fmamk_f32 v134, v134, 0x3c000000, v234
	v_fmamk_f32 v136, v136, 0x3c000000, v234
	v_fmamk_f32 v137, v137, 0x3c000000, v234
	v_rsq_f32_e32 v146, v146
	v_rsq_f32_e32 v145, v145
	v_rsq_f32_e32 v144, v144
	v_rsq_f32_e32 v143, v143
	v_rsq_f32_e32 v142, v142
	v_rsq_f32_e32 v141, v141
	v_rsq_f32_e32 v140, v140
	v_rsq_f32_e32 v139, v139
	v_rsq_f32_e32 v138, v138
	v_rsq_f32_e32 v132, v132
	v_rsq_f32_e32 v126, v126
	v_rsq_f32_e32 v118, v118
	v_rsq_f32_e32 v134, v134
	v_rsq_f32_e32 v136, v136
	v_rsq_f32_e32 v137, v137
	v_mul_f32_e32 v146, 0x3f4ccccd, v146
	v_mul_f32_e32 v145, 0x3f4ccccd, v145
	v_mul_f32_e32 v144, 0x3f4ccccd, v144
	v_mul_f32_e32 v143, 0x3f4ccccd, v143
	v_mul_f32_e32 v142, 0x3f4ccccd, v142
	v_mul_f32_e32 v141, 0x3f4ccccd, v141
	v_mul_f32_e32 v140, 0x3f4ccccd, v140
	v_mul_f32_e32 v139, 0x3f4ccccd, v139
	v_mul_f32_e32 v138, 0x3f4ccccd, v138
	v_mul_f32_e32 v132, 0x3f4ccccd, v132
	v_mul_f32_e32 v126, 0x3f4ccccd, v126
	v_mul_f32_e32 v153, 0x3f4ccccd, v118
	v_mul_f32_e32 v152, 0x3f4ccccd, v134
	v_mul_f32_e32 v134, 0x3f4ccccd, v136
	v_mul_f32_e32 v118, 0x3f4ccccd, v137
	v_mul_f32_e32 v78, v78, v146
	v_mul_f32_e32 v77, v77, v145
	v_mul_f32_e32 v76, v76, v144
	v_mul_f32_e32 v75, v75, v143
	v_mul_f32_e32 v74, v74, v142
	v_mul_f32_e32 v73, v73, v141
	v_mul_f32_e32 v31, v31, v140
	v_mul_f32_e32 v30, v30, v139
	v_mul_f32_e32 v29, v29, v138
	v_mul_f32_e32 v28, v28, v132
	v_mul_f32_e32 v27, v27, v126
	v_mul_f32_e32 v26, v26, v153
	v_mul_f32_e32 v25, v25, v152
	v_mul_f32_e32 v24, v24, v134
	v_mul_f32_e32 v23, v23, v118
	global_load_dword v136, v[202:203], off
	global_load_dword v137, v[202:203], off offset:128
	global_load_dword v147, v[202:203], off offset:256
	global_load_dword v148, v[202:203], off offset:384
	v_fmamk_f32 v32, v32, 0x3c000000, v234
	v_rsq_f32_e32 v32, v32
	s_waitcnt vmcnt(3)
	v_mul_f32_e32 v78, v78, v136
	v_bfe_u32 v149, v78, 16, 1
	v_add3_u32 v78, v78, v149, s70
	global_store_short_d16_hi v[172:173], v78, off offset:1024
	v_mul_f32_e32 v78, v95, v146
	s_waitcnt vmcnt(3)
	v_mul_f32_e32 v78, v78, v137
	v_bfe_u32 v95, v78, 16, 1
	v_add3_u32 v78, v78, v95, s70
	global_store_short_d16_hi v[172:173], v78, off offset:1088
	v_mul_f32_e32 v78, v116, v146
	s_waitcnt vmcnt(3)
	v_mul_f32_e32 v78, v78, v147
	v_bfe_u32 v95, v78, 16, 1
	v_add3_u32 v78, v78, v95, s70
	global_store_short_d16_hi v[172:173], v78, off offset:1152
	v_mul_f32_e32 v78, v117, v146
	s_waitcnt vmcnt(3)
; __device__ __forceinline__ unsigned f2bf(float f) { unsigned u = __builtin_bit_cast(unsigned, f); return (u + 0x7fffu + ((u >> 16) & 1u)) >> 16; }
; __device__ __forceinline__ int crow(int r, int hi) { return (r & 3) + 8 * (r >> 2) + 4 * hi; }
; __device__ __forceinline__ int crow(int r, int hi) { return (r & 3) + 8 * (r >> 2) + 4 * hi; }
; template <int NCB, bool DIFF, bool STAT>
; __device__ __forceinline__ void attn_unit(LAS char* lds, const Params& P, int s, int head, int qb, float sref) {
;     ...
;                 for (int r = 0; r < 16; ++r) { const int orow = crow(r, hi);
; #pragma unroll
;                     for (int d0 = 0; d0 < NCB; ++d0) mixw[(size_t)orow * DM + 512 + head * 128 + d0 * 32 + r32] = (bf16)f2bf(o[d0][r] * ss[r] * gs[d0]); }
	v_mul_f32_e32 v78, v78, v148
	v_bfe_u32 v95, v78, 16, 1
	v_add3_u32 v78, v78, v95, s70
	v_mul_f32_e32 v77, v77, v136
	global_store_short_d16_hi v[172:173], v78, off offset:1216
	v_bfe_u32 v78, v77, 16, 1
	v_add3_u32 v77, v77, v78, s70
	global_store_short_d16_hi v[172:173], v77, off offset:3072
	v_mul_f32_e32 v77, v96, v145
	v_mul_f32_e32 v77, v77, v137
	v_bfe_u32 v78, v77, 16, 1
	v_add3_u32 v77, v77, v78, s70
	global_store_short_d16_hi v[172:173], v77, off offset:3136
	v_mul_f32_e32 v77, v115, v145
	v_mul_f32_e32 v77, v77, v147
	v_bfe_u32 v78, v77, 16, 1
	v_add3_u32 v77, v77, v78, s70
	global_store_short_d16_hi v[172:173], v77, off offset:3200
	v_mul_f32_e32 v77, v121, v145
	v_mul_f32_e32 v77, v77, v148
	v_bfe_u32 v78, v77, 16, 1
	v_add3_u32 v77, v77, v78, s70
	v_mul_f32_e32 v76, v76, v136
	global_store_short_d16_hi v[172:173], v77, off offset:3264
	v_bfe_u32 v77, v76, 16, 1
	v_add3_u32 v76, v76, v77, s70
	global_store_short_d16_hi v[174:175], v76, off
	v_mul_f32_e32 v76, v97, v144
	v_mul_f32_e32 v76, v76, v137
	v_bfe_u32 v77, v76, 16, 1
	v_add3_u32 v76, v76, v77, s70
	global_store_short_d16_hi v[174:175], v76, off offset:64
	v_mul_f32_e32 v76, v114, v144
	v_mul_f32_e32 v76, v76, v147
	v_bfe_u32 v77, v76, 16, 1
	v_add3_u32 v76, v76, v77, s70
	global_store_short_d16_hi v[174:175], v76, off offset:128
	v_mul_f32_e32 v76, v119, v144
	v_mul_f32_e32 v76, v76, v148
	v_bfe_u32 v77, v76, 16, 1
	v_add3_u32 v76, v76, v77, s70
	v_mul_f32_e32 v75, v75, v136
	global_store_short_d16_hi v[174:175], v76, off offset:192
	v_bfe_u32 v76, v75, 16, 1
	v_add3_u32 v75, v75, v76, s70
	global_store_short_d16_hi v[176:177], v75, off
	v_mul_f32_e32 v75, v94, v143
	v_mul_f32_e32 v75, v75, v137
	v_bfe_u32 v76, v75, 16, 1
	v_add3_u32 v75, v75, v76, s70
	global_store_short_d16_hi v[176:177], v75, off offset:64
	v_mul_f32_e32 v75, v113, v143
	v_mul_f32_e32 v75, v75, v147
	v_bfe_u32 v76, v75, 16, 1
	v_add3_u32 v75, v75, v76, s70
	global_store_short_d16_hi v[176:177], v75, off offset:128
	v_mul_f32_e32 v75, v122, v143
	v_mul_f32_e32 v75, v75, v148
	v_bfe_u32 v76, v75, 16, 1
	v_add3_u32 v75, v75, v76, s70
	v_mul_f32_e32 v74, v74, v136
	global_store_short_d16_hi v[176:177], v75, off offset:192
	v_bfe_u32 v75, v74, 16, 1
	v_add3_u32 v74, v74, v75, s70
	global_store_short_d16_hi v[178:179], v74, off
	v_mul_f32_e32 v74, v93, v142
	v_mul_f32_e32 v74, v74, v137
	v_bfe_u32 v75, v74, 16, 1
	v_add3_u32 v74, v74, v75, s70
	global_store_short_d16_hi v[178:179], v74, off offset:64
	v_mul_f32_e32 v74, v112, v142
	v_mul_f32_e32 v74, v74, v147
	v_bfe_u32 v75, v74, 16, 1
	v_add3_u32 v74, v74, v75, s70
	global_store_short_d16_hi v[178:179], v74, off offset:128
	v_mul_f32_e32 v74, v120, v142
	v_mul_f32_e32 v74, v74, v148
	v_bfe_u32 v75, v74, 16, 1
	v_add3_u32 v74, v74, v75, s70
	v_mul_f32_e32 v73, v73, v136
	global_store_short_d16_hi v[178:179], v74, off offset:192
	v_bfe_u32 v74, v73, 16, 1
	v_add3_u32 v73, v73, v74, s70
	global_store_short_d16_hi v[180:181], v73, off
	v_mul_f32_e32 v73, v92, v141
	v_mul_f32_e32 v73, v73, v137
	v_bfe_u32 v74, v73, 16, 1
	v_add3_u32 v73, v73, v74, s70
	global_store_short_d16_hi v[180:181], v73, off offset:64
	v_mul_f32_e32 v73, v111, v141
	v_mul_f32_e32 v73, v73, v147
	v_bfe_u32 v74, v73, 16, 1
	v_add3_u32 v73, v73, v74, s70
	global_store_short_d16_hi v[180:181], v73, off offset:128
	v_mul_f32_e32 v73, v124, v141
	v_mul_f32_e32 v73, v73, v148
	v_bfe_u32 v74, v73, 16, 1
	v_add3_u32 v73, v73, v74, s70
	v_mul_f32_e32 v31, v31, v136
	global_store_short_d16_hi v[180:181], v73, off offset:192
	v_bfe_u32 v73, v31, 16, 1
	v_add3_u32 v31, v31, v73, s70
	global_store_short_d16_hi v[182:183], v31, off
	v_mul_f32_e32 v31, v91, v140
	v_mul_f32_e32 v31, v31, v137
	v_bfe_u32 v73, v31, 16, 1
	v_add3_u32 v31, v31, v73, s70
	global_store_short_d16_hi v[182:183], v31, off offset:64
	v_mul_f32_e32 v31, v110, v140
	v_mul_f32_e32 v31, v31, v147
	v_bfe_u32 v73, v31, 16, 1
	v_add3_u32 v31, v31, v73, s70
	global_store_short_d16_hi v[182:183], v31, off offset:128
	v_mul_f32_e32 v31, v123, v140
	v_mul_f32_e32 v31, v31, v148
	v_bfe_u32 v73, v31, 16, 1
	v_add3_u32 v31, v31, v73, s70
	v_mul_f32_e32 v30, v30, v136
	global_store_short_d16_hi v[182:183], v31, off offset:192
	v_bfe_u32 v31, v30, 16, 1
	v_add3_u32 v30, v30, v31, s70
	global_store_short_d16_hi v[184:185], v30, off
	v_mul_f32_e32 v30, v90, v139
	v_mul_f32_e32 v30, v30, v137
	v_bfe_u32 v31, v30, 16, 1
	v_add3_u32 v30, v30, v31, s70
	global_store_short_d16_hi v[184:185], v30, off offset:64
	v_mul_f32_e32 v30, v109, v139
	v_mul_f32_e32 v30, v30, v147
	v_bfe_u32 v31, v30, 16, 1
	v_add3_u32 v30, v30, v31, s70
	global_store_short_d16_hi v[184:185], v30, off offset:128
	v_mul_f32_e32 v30, v127, v139
	v_mul_f32_e32 v30, v30, v148
	v_bfe_u32 v31, v30, 16, 1
	v_add3_u32 v30, v30, v31, s70
	v_mul_f32_e32 v29, v29, v136
	global_store_short_d16_hi v[184:185], v30, off offset:192
	v_bfe_u32 v30, v29, 16, 1
	v_add3_u32 v29, v29, v30, s70
	global_store_short_d16_hi v[186:187], v29, off
	v_mul_f32_e32 v29, v89, v138
	v_mul_f32_e32 v29, v29, v137
	v_bfe_u32 v30, v29, 16, 1
; __device__ __forceinline__ unsigned f2bf(float f) { unsigned u = __builtin_bit_cast(unsigned, f); return (u + 0x7fffu + ((u >> 16) & 1u)) >> 16; }
; __device__ __forceinline__ int crow(int r, int hi) { return (r & 3) + 8 * (r >> 2) + 4 * hi; }
; __device__ __forceinline__ int crow(int r, int hi) { return (r & 3) + 8 * (r >> 2) + 4 * hi; }
; template <int NCB, bool DIFF, bool STAT>
; __device__ __forceinline__ void attn_unit(LAS char* lds, const Params& P, int s, int head, int qb, float sref) {
;     ...
;                 for (int r = 0; r < 16; ++r) { const int orow = crow(r, hi);
; #pragma unroll
;                     for (int d0 = 0; d0 < NCB; ++d0) mixw[(size_t)orow * DM + 512 + head * 128 + d0 * 32 + r32] = (bf16)f2bf(o[d0][r] * ss[r] * gs[d0]); }
	v_add3_u32 v29, v29, v30, s70
	global_store_short_d16_hi v[186:187], v29, off offset:64
	v_mul_f32_e32 v29, v108, v138
	v_mul_f32_e32 v29, v29, v147
	v_bfe_u32 v30, v29, 16, 1
	v_add3_u32 v29, v29, v30, s70
	global_store_short_d16_hi v[186:187], v29, off offset:128
	v_mul_f32_e32 v29, v125, v138
	v_mul_f32_e32 v29, v29, v148
	v_bfe_u32 v30, v29, 16, 1
	v_add3_u32 v29, v29, v30, s70
	v_mul_f32_e32 v28, v28, v136
	global_store_short_d16_hi v[186:187], v29, off offset:192
	v_bfe_u32 v29, v28, 16, 1
	v_add3_u32 v28, v28, v29, s70
	global_store_short_d16_hi v[188:189], v28, off
	v_mul_f32_e32 v28, v81, v132
	v_mul_f32_e32 v28, v28, v137
	v_bfe_u32 v29, v28, 16, 1
	v_add3_u32 v28, v28, v29, s70
	global_store_short_d16_hi v[188:189], v28, off offset:64
	v_mul_f32_e32 v28, v107, v132
	v_mul_f32_e32 v28, v28, v147
	v_bfe_u32 v29, v28, 16, 1
	v_add3_u32 v28, v28, v29, s70
	global_store_short_d16_hi v[188:189], v28, off offset:128
	v_mul_f32_e32 v28, v129, v132
	v_mul_f32_e32 v28, v28, v148
	v_bfe_u32 v29, v28, 16, 1
	v_add3_u32 v28, v28, v29, s70
	v_mul_f32_e32 v27, v27, v136
	global_store_short_d16_hi v[188:189], v28, off offset:192
	v_bfe_u32 v28, v27, 16, 1
	v_add3_u32 v27, v27, v28, s70
	global_store_short_d16_hi v[190:191], v27, off
	v_mul_f32_e32 v27, v80, v126
	v_mul_f32_e32 v27, v27, v137
	v_bfe_u32 v28, v27, 16, 1
	v_add3_u32 v27, v27, v28, s70
	global_store_short_d16_hi v[190:191], v27, off offset:64
	v_mul_f32_e32 v27, v106, v126
	v_mul_f32_e32 v27, v27, v147
	v_bfe_u32 v28, v27, 16, 1
	v_add3_u32 v27, v27, v28, s70
	global_store_short_d16_hi v[190:191], v27, off offset:128
	v_mul_f32_e32 v27, v128, v126
	v_mul_f32_e32 v27, v27, v148
	v_bfe_u32 v28, v27, 16, 1
	v_add3_u32 v27, v27, v28, s70
	v_mul_f32_e32 v26, v26, v136
	global_store_short_d16_hi v[190:191], v27, off offset:192
	v_bfe_u32 v27, v26, 16, 1
	v_add3_u32 v26, v26, v27, s70
	global_store_short_d16_hi v[192:193], v26, off
	v_mul_f32_e32 v26, v79, v153
	v_mul_f32_e32 v26, v26, v137
	v_bfe_u32 v27, v26, 16, 1
	v_add3_u32 v26, v26, v27, s70
	global_store_short_d16_hi v[192:193], v26, off offset:64
	v_mul_f32_e32 v26, v105, v153
	v_mul_f32_e32 v26, v26, v147
	v_bfe_u32 v27, v26, 16, 1
	v_add3_u32 v26, v26, v27, s70
	global_store_short_d16_hi v[192:193], v26, off offset:128
	v_mul_f32_e32 v26, v131, v153
	v_mul_f32_e32 v26, v26, v148
	v_bfe_u32 v27, v26, 16, 1
	v_add3_u32 v26, v26, v27, s70
	v_mul_f32_e32 v25, v25, v136
	global_store_short_d16_hi v[192:193], v26, off offset:192
	v_bfe_u32 v26, v25, 16, 1
	v_add3_u32 v25, v25, v26, s70
	global_store_short_d16_hi v[194:195], v25, off
	v_mul_f32_e32 v25, v98, v152
	v_mul_f32_e32 v25, v25, v137
	v_bfe_u32 v26, v25, 16, 1
	v_add3_u32 v25, v25, v26, s70
	global_store_short_d16_hi v[194:195], v25, off offset:64
	v_mul_f32_e32 v25, v104, v152
	v_mul_f32_e32 v25, v25, v147
	v_bfe_u32 v26, v25, 16, 1
	v_add3_u32 v25, v25, v26, s70
	global_store_short_d16_hi v[194:195], v25, off offset:128
	v_mul_f32_e32 v25, v130, v152
	v_mul_f32_e32 v25, v25, v148
	v_bfe_u32 v26, v25, 16, 1
	v_add3_u32 v25, v25, v26, s70
	v_mul_f32_e32 v24, v24, v136
	global_store_short_d16_hi v[194:195], v25, off offset:192
	v_bfe_u32 v25, v24, 16, 1
	v_add3_u32 v24, v24, v25, s70
	global_store_short_d16_hi v[196:197], v24, off
	v_mul_f32_e32 v24, v99, v134
	v_mul_f32_e32 v24, v24, v137
	v_bfe_u32 v25, v24, 16, 1
	v_add3_u32 v24, v24, v25, s70
	global_store_short_d16_hi v[196:197], v24, off offset:64
	v_mul_f32_e32 v24, v103, v134
	v_mul_f32_e32 v24, v24, v147
	v_bfe_u32 v25, v24, 16, 1
	v_add3_u32 v24, v24, v25, s70
	global_store_short_d16_hi v[196:197], v24, off offset:128
	v_mul_f32_e32 v24, v135, v134
	v_mul_f32_e32 v24, v24, v148
	v_bfe_u32 v25, v24, 16, 1
	v_add3_u32 v24, v24, v25, s70
	v_mul_f32_e32 v23, v136, v23
	global_store_short_d16_hi v[196:197], v24, off offset:192
	v_bfe_u32 v24, v23, 16, 1
	v_add3_u32 v23, v23, v24, s70
	global_store_short_d16_hi v[198:199], v23, off
	v_mul_f32_e32 v23, v100, v118
	v_mul_f32_e32 v23, v23, v137
	v_bfe_u32 v24, v23, 16, 1
	v_add3_u32 v23, v23, v24, s70
	global_store_short_d16_hi v[198:199], v23, off offset:64
	v_mul_f32_e32 v23, v102, v118
	v_mul_f32_e32 v23, v23, v147
	v_bfe_u32 v24, v23, 16, 1
	v_add3_u32 v23, v23, v24, s70
	global_store_short_d16_hi v[198:199], v23, off offset:128
	v_mul_f32_e32 v23, v133, v118
	v_mul_f32_e32 v32, 0x3f4ccccd, v32
	v_mul_f32_e32 v23, v23, v148
	v_bfe_u32 v24, v23, 16, 1
	v_mul_f32_e32 v22, v22, v32
	v_add3_u32 v23, v23, v24, s70
	v_mul_f32_e32 v22, v136, v22
	global_store_short_d16_hi v[198:199], v23, off offset:192
	v_bfe_u32 v23, v22, 16, 1
	v_add3_u32 v22, v22, v23, s70
	global_store_short_d16_hi v[200:201], v22, off
	v_mul_f32_e32 v22, v101, v32
	v_mul_f32_e32 v22, v137, v22
	v_bfe_u32 v23, v22, 16, 1
	v_mul_f32_e32 v2, v2, v32
	v_add3_u32 v22, v22, v23, s70
	v_mul_f32_e32 v2, v147, v2
	global_store_short_d16_hi v[200:201], v22, off offset:64
	v_bfe_u32 v22, v2, 16, 1
	v_add3_u32 v2, v2, v22, s70
	global_store_short_d16_hi v[200:201], v2, off offset:128
	v_mul_f32_e32 v2, v3, v32
	v_mul_f32_e32 v2, v148, v2
